# GEMM load segments with six LDS-DMA loads issue the DMA loads before the LDS fragment reads
# baseline (speedup 1.0000x reference)
; #define PG8_STAGE(bufoff, gbase, voff) do { _Pragma("unroll") for (int _i = 0; _i < 2; ++_i) \
;         __builtin_amdgcn_global_load_lds((const unsigned*)((const char*)(gbase) + (voff)[_i]), (PG8_LAS unsigned*)(lds + (bufoff) + ldsw + _i * 8192), 16, 0, 0); } while (0)
; #define PG8_LDA(dst, b, h) do { _Pragma("unroll") for (int m = 0; m < 4; ++m) _Pragma("unroll") for (int k = 0; k < 2; ++k) dst[m][k] = *(const PG8_LAS bf16x8*)(lds + PG8_SA(b, h) + aoff + m * 2048 + k * 1024); } while (0)
; #define PG8_LDB(dst, b, h) do { _Pragma("unroll") for (int n = 0; n < 2; ++n) _Pragma("unroll") for (int k = 0; k < 2; ++k) dst[n][k] = *(const PG8_LAS bf16x8*)(lds + PG8_SB(b, h) + boff + n * 2048 + k * 1024); } while (0)
; #define PG8_MMA(ai, bj, At, Bt) do { __builtin_amdgcn_s_setprio(1); _Pragma("unroll") for (int m = 0; m < 4; ++m) _Pragma("unroll") for (int n = 0; n < 2; ++n) _Pragma("unroll") for (int k = 0; k < 2; ++k) \
;         acc[ai][bj][m][n] = __builtin_amdgcn_mfma_f32_16x16x32_bf16(Bt[n][k], At[m][k], acc[ai][bj][m][n], 0, 0, 0); __builtin_amdgcn_s_setprio(0); } while (0)
; #define PG8_WAIT_V(n) asm volatile("s_waitcnt vmcnt(" #n ")" ::: "memory")
; #define PG8_WAIT_L(n) asm volatile("s_waitcnt lgkmcnt(" #n ")" ::: "memory")
; template <class Epi, class Sched, bool ALIGN_EPI = false, bool SP2 = false>
; __device__ __forceinline__ void gemm_phase(PG8_LAS unsigned char* lds, const Gemm g, const Sched& S, const Epi& E) {
;     ...
;             const bool last = (t == nt - 2);
;             const char* a1 = cA + (size_t)(t + 1) * kstep;
;             const char* a2 = last ? nA : cA + (size_t)(t + 2) * kstep; const char* b2 = last ? nB : cB + (size_t)(t + 2) * kstep;
;             const char* a3 = a2 + kstep; const char* b3 = b2 + kstep;
;             if (last && has_next) S.a_ready(nxt);
;             if constexpr (SP2) {
;             PG8_LDB(B0, 0, 0); PG8_LDB(B1, 0, 1); PG8_SCHED; PG8_LDA(At, 0, 0); PG8_STAGE(PG8_SA(1, 1), a1 + hstep, voffA);
;             PG8_WAIT_V(8); PG8_WAIT_L(0); PG8_BAR; PG8_MMA(0, 0, At, B0); PG8_MMA(0, 1, At, B1); PG8_BAR; PG8_SCHED;
;             PG8_LDA(At, 0, 1); PG8_STAGE(PG8_SB(0, 0), b2, voffB); PG8_STAGE(PG8_SB(0, 1), b2 + hstep, voffB); PG8_STAGE(PG8_SA(0, 0), a2, voffA);
;             PG8_WAIT_V(8); PG8_WAIT_L(0); PG8_BAR; PG8_MMA(1, 0, At, B0); PG8_MMA(1, 1, At, B1); PG8_BAR; PG8_SCHED;
.LBB0_244:
	ds_read_b128 v[128:131], v169
	ds_read_b128 v[156:159], v169 offset:1024
	ds_read_b128 v[160:163], v169 offset:2048
	ds_read_b128 v[164:167], v169 offset:3072
	ds_read_b128 v[176:179], v170
	ds_read_b128 v[180:183], v170 offset:1024
	ds_read_b128 v[188:191], v170 offset:2048
	ds_read_b128 v[192:195], v170 offset:3072
	s_add_u32 s0, s4, 0xfff80080
	s_addc_u32 s1, s5, -1
	s_cmp_eq_u32 vcc_hi, 28
	s_cselect_b32 s9, s41, s1
	s_cselect_b32 s8, s51, s0
	s_cselect_b32 s7, s43, vcc_lo
	s_cselect_b32 s6, s56, s57
	s_add_i32 m0, s49, 0xc000
	ds_read_b128 v[196:199], v171
	ds_read_b128 v[200:203], v171 offset:1024
	ds_read_b128 v[204:207], v171 offset:2048
	ds_read_b128 v[208:211], v171 offset:3072
	ds_read_b128 v[212:215], v171 offset:4096
	ds_read_b128 v[216:219], v171 offset:5120
	ds_read_b128 v[220:223], v171 offset:6144
	ds_read_b128 v[224:227], v171 offset:7168
	global_load_lds_dwordx4 v144, s[4:5]
	s_add_i32 m0, s49, 0xe000
	s_nop 0
	global_load_lds_dwordx4 v146, s[4:5]
	s_waitcnt vmcnt(8)
	s_waitcnt lgkmcnt(0)
	s_barrier
	s_setprio 1
	s_waitcnt lgkmcnt(0)
	v_mfma_f32_16x16x32_bf16 v[124:127], v[128:131], v[196:199], v[124:127]
	v_mfma_f32_16x16x32_bf16 v[120:123], v[160:163], v[196:199], v[120:123]
	v_mfma_f32_16x16x32_bf16 v[108:111], v[128:131], v[204:207], v[108:111]
	v_mfma_f32_16x16x32_bf16 v[104:107], v[160:163], v[204:207], v[104:107]
	v_mfma_f32_16x16x32_bf16 v[92:95], v[128:131], v[212:215], v[92:95]
	v_mfma_f32_16x16x32_bf16 v[88:91], v[160:163], v[212:215], v[88:91]
	v_mfma_f32_16x16x32_bf16 v[76:79], v[128:131], v[220:223], v[76:79]
	v_mfma_f32_16x16x32_bf16 v[72:75], v[160:163], v[220:223], v[72:75]
	v_mfma_f32_16x16x32_bf16 v[124:127], v[156:159], v[200:203], v[124:127]
	v_mfma_f32_16x16x32_bf16 v[120:123], v[164:167], v[200:203], v[120:123]
	v_mfma_f32_16x16x32_bf16 v[108:111], v[156:159], v[208:211], v[108:111]
	v_mfma_f32_16x16x32_bf16 v[104:107], v[164:167], v[208:211], v[104:107]
	v_mfma_f32_16x16x32_bf16 v[92:95], v[156:159], v[216:219], v[92:95]
	v_mfma_f32_16x16x32_bf16 v[88:91], v[164:167], v[216:219], v[88:91]
	v_mfma_f32_16x16x32_bf16 v[76:79], v[156:159], v[224:227], v[76:79]
	v_mfma_f32_16x16x32_bf16 v[72:75], v[164:167], v[224:227], v[72:75]
	v_mfma_f32_16x16x32_bf16 v[116:119], v[176:179], v[196:199], v[116:119]
	v_mfma_f32_16x16x32_bf16 v[112:115], v[188:191], v[196:199], v[112:115]
	v_mfma_f32_16x16x32_bf16 v[100:103], v[176:179], v[204:207], v[100:103]
	v_mfma_f32_16x16x32_bf16 v[96:99], v[188:191], v[204:207], v[96:99]
	v_mfma_f32_16x16x32_bf16 v[84:87], v[176:179], v[212:215], v[84:87]
	v_mfma_f32_16x16x32_bf16 v[80:83], v[188:191], v[212:215], v[80:83]
	v_mfma_f32_16x16x32_bf16 v[68:71], v[176:179], v[220:223], v[68:71]
	v_mfma_f32_16x16x32_bf16 v[64:67], v[188:191], v[220:223], v[64:67]
	v_mfma_f32_16x16x32_bf16 v[116:119], v[180:183], v[200:203], v[116:119]
	v_mfma_f32_16x16x32_bf16 v[112:115], v[192:195], v[200:203], v[112:115]
	v_mfma_f32_16x16x32_bf16 v[100:103], v[180:183], v[208:211], v[100:103]
	v_mfma_f32_16x16x32_bf16 v[96:99], v[192:195], v[208:211], v[96:99]
	v_mfma_f32_16x16x32_bf16 v[84:87], v[180:183], v[216:219], v[84:87]
	v_mfma_f32_16x16x32_bf16 v[80:83], v[192:195], v[216:219], v[80:83]
	v_mfma_f32_16x16x32_bf16 v[68:71], v[180:183], v[224:227], v[68:71]
	v_mfma_f32_16x16x32_bf16 v[64:67], v[192:195], v[224:227], v[64:67]
	s_setprio 0
	s_barrier
	s_add_u32 s98, s6, s26
	s_addc_u32 s99, s7, s27
	s_add_u32 s100, s8, s26
	s_addc_u32 s101, s9, s27
	s_add_i32 s0, s70, s58
	s_mov_b32 m0, s0
	s_nop 0
	global_load_lds_dwordx4 v136, s[6:7]
	s_add_i32 m0, s0, 0x2000
	s_add_u32 s0, s6, 0x80000
	s_addc_u32 s1, s7, 0
	s_add_i32 s83, s72, s58
	global_load_lds_dwordx4 v140, s[6:7]
	s_mov_b32 m0, s83
	s_nop 0
	global_load_lds_dwordx4 v136, s[0:1]
	s_add_i32 m0, s83, 0x2000
	s_nop 0
	global_load_lds_dwordx4 v140, s[0:1]
	s_mov_b32 m0, s49
	s_nop 0
	global_load_lds_dwordx4 v134, s[8:9]
	s_mov_b32 m0, s59
	s_nop 0
	global_load_lds_dwordx4 v138, s[8:9]
	ds_read_b128 v[196:199], v171 offset:16384
	ds_read_b128 v[200:203], v171 offset:17408
	ds_read_b128 v[204:207], v171 offset:18432
	ds_read_b128 v[208:211], v171 offset:19456
	ds_read_b128 v[212:215], v171 offset:20480
	ds_read_b128 v[216:219], v171 offset:21504
	ds_read_b128 v[220:223], v171 offset:22528
	ds_read_b128 v[224:227], v171 offset:23552
	s_waitcnt vmcnt(8)
	s_waitcnt lgkmcnt(0)
	s_barrier
	s_setprio 1
	s_waitcnt lgkmcnt(0)
	v_mfma_f32_16x16x32_bf16 v[60:63], v[128:131], v[196:199], v[60:63]
	v_mfma_f32_16x16x32_bf16 v[56:59], v[160:163], v[196:199], v[56:59]
	v_mfma_f32_16x16x32_bf16 v[44:47], v[128:131], v[204:207], v[44:47]
	v_mfma_f32_16x16x32_bf16 v[40:43], v[160:163], v[204:207], v[40:43]
	v_mfma_f32_16x16x32_bf16 v[28:31], v[128:131], v[212:215], v[28:31]
	v_mfma_f32_16x16x32_bf16 v[24:27], v[160:163], v[212:215], v[24:27]
	v_mfma_f32_16x16x32_bf16 v[12:15], v[128:131], v[220:223], v[12:15]
	v_mfma_f32_16x16x32_bf16 v[8:11], v[160:163], v[220:223], v[8:11]
	v_mfma_f32_16x16x32_bf16 v[60:63], v[156:159], v[200:203], v[60:63]
	v_mfma_f32_16x16x32_bf16 v[56:59], v[164:167], v[200:203], v[56:59]
	v_mfma_f32_16x16x32_bf16 v[44:47], v[156:159], v[208:211], v[44:47]
	v_mfma_f32_16x16x32_bf16 v[40:43], v[164:167], v[208:211], v[40:43]
	v_mfma_f32_16x16x32_bf16 v[28:31], v[156:159], v[216:219], v[28:31]
	v_mfma_f32_16x16x32_bf16 v[24:27], v[164:167], v[216:219], v[24:27]
	v_mfma_f32_16x16x32_bf16 v[12:15], v[156:159], v[224:227], v[12:15]
	v_mfma_f32_16x16x32_bf16 v[8:11], v[164:167], v[224:227], v[8:11]
	v_mfma_f32_16x16x32_bf16 v[52:55], v[176:179], v[196:199], v[52:55]
	v_mfma_f32_16x16x32_bf16 v[48:51], v[188:191], v[196:199], v[48:51]
	v_mfma_f32_16x16x32_bf16 v[36:39], v[176:179], v[204:207], v[36:39]
	v_mfma_f32_16x16x32_bf16 v[32:35], v[188:191], v[204:207], v[32:35]
	v_mfma_f32_16x16x32_bf16 v[20:23], v[176:179], v[212:215], v[20:23]
	v_mfma_f32_16x16x32_bf16 v[16:19], v[188:191], v[212:215], v[16:19]
	v_mfma_f32_16x16x32_bf16 v[4:7], v[176:179], v[220:223], v[4:7]
	v_mfma_f32_16x16x32_bf16 v[0:3], v[188:191], v[220:223], v[0:3]
	v_mfma_f32_16x16x32_bf16 v[52:55], v[180:183], v[200:203], v[52:55]
	v_mfma_f32_16x16x32_bf16 v[48:51], v[192:195], v[200:203], v[48:51]
	v_mfma_f32_16x16x32_bf16 v[36:39], v[180:183], v[208:211], v[36:39]
	v_mfma_f32_16x16x32_bf16 v[32:35], v[192:195], v[208:211], v[32:35]
	v_mfma_f32_16x16x32_bf16 v[20:23], v[180:183], v[216:219], v[20:23]
	v_mfma_f32_16x16x32_bf16 v[16:19], v[192:195], v[216:219], v[16:19]
	v_mfma_f32_16x16x32_bf16 v[4:7], v[180:183], v[224:227], v[4:7]
	v_mfma_f32_16x16x32_bf16 v[0:3], v[192:195], v[224:227], v[0:3]
	s_setprio 0
	s_barrier
; #define PG8_STAGE(bufoff, gbase, voff) do { _Pragma("unroll") for (int _i = 0; _i < 2; ++_i) \
;         __builtin_amdgcn_global_load_lds((const unsigned*)((const char*)(gbase) + (voff)[_i]), (PG8_LAS unsigned*)(lds + (bufoff) + ldsw + _i * 8192), 16, 0, 0); } while (0)
; #define PG8_LDA(dst, b, h) do { _Pragma("unroll") for (int m = 0; m < 4; ++m) _Pragma("unroll") for (int k = 0; k < 2; ++k) dst[m][k] = *(const PG8_LAS bf16x8*)(lds + PG8_SA(b, h) + aoff + m * 2048 + k * 1024); } while (0)
; #define PG8_LDB(dst, b, h) do { _Pragma("unroll") for (int n = 0; n < 2; ++n) _Pragma("unroll") for (int k = 0; k < 2; ++k) dst[n][k] = *(const PG8_LAS bf16x8*)(lds + PG8_SB(b, h) + boff + n * 2048 + k * 1024); } while (0)
; #define PG8_MMA(ai, bj, At, Bt) do { __builtin_amdgcn_s_setprio(1); _Pragma("unroll") for (int m = 0; m < 4; ++m) _Pragma("unroll") for (int n = 0; n < 2; ++n) _Pragma("unroll") for (int k = 0; k < 2; ++k) \
;         acc[ai][bj][m][n] = __builtin_amdgcn_mfma_f32_16x16x32_bf16(Bt[n][k], At[m][k], acc[ai][bj][m][n], 0, 0, 0); __builtin_amdgcn_s_setprio(0); } while (0)
; #define PG8_WAIT_V(n) asm volatile("s_waitcnt vmcnt(" #n ")" ::: "memory")
; #define PG8_WAIT_L(n) asm volatile("s_waitcnt lgkmcnt(" #n ")" ::: "memory")
; #define PG8_BAR __builtin_amdgcn_s_barrier()
; #define PG8_SCHED __builtin_amdgcn_sched_barrier(0)
; template <class Epi, class Sched, bool ALIGN_EPI = false, bool SP2 = false>
; __device__ __forceinline__ void gemm_phase(PG8_LAS unsigned char* lds, const Gemm g, const Sched& S, const Epi& E) {
;     ...
;             PG8_LDB(B0, 1, 0); PG8_LDB(B1, 1, 1); PG8_SCHED; PG8_LDA(At, 1, 0); PG8_STAGE(PG8_SA(0, 1), a2 + hstep, voffA);
;             PG8_WAIT_V(8); PG8_WAIT_L(0); PG8_BAR; PG8_MMA(0, 0, At, B0); PG8_MMA(0, 1, At, B1); PG8_BAR; PG8_SCHED;
;             PG8_LDA(At, 1, 1); PG8_STAGE(PG8_SB(1, 0), b3, voffB); PG8_STAGE(PG8_SB(1, 1), b3 + hstep, voffB); PG8_STAGE(PG8_SA(1, 0), a3, voffA);
;             PG8_WAIT_V(8); PG8_WAIT_L(0); PG8_BAR; PG8_MMA(1, 0, At, B0); PG8_MMA(1, 1, At, B1); PG8_BAR; PG8_SCHED;
	s_add_i32 s83, 0, 0x18000
	v_add_u32_e32 v142, s83, v168
	s_add_i32 s88, 0, 0x1c000
	ds_read_b128 v[128:131], v142
	ds_read_b128 v[156:159], v142 offset:1024
	ds_read_b128 v[160:163], v142 offset:2048
	ds_read_b128 v[164:167], v142 offset:3072
	v_add_u32_e32 v142, s88, v168
	ds_read_b128 v[176:179], v142
	ds_read_b128 v[180:183], v142 offset:1024
	ds_read_b128 v[188:191], v142 offset:2048
	ds_read_b128 v[192:195], v142 offset:3072
	s_add_u32 s0, s8, 0x80000
	s_addc_u32 s1, s9, 0
	s_mov_b32 m0, s73
	ds_read_b128 v[196:199], v171 offset:32768
	ds_read_b128 v[200:203], v171 offset:33792
	ds_read_b128 v[204:207], v171 offset:34816
	ds_read_b128 v[208:211], v171 offset:35840
	ds_read_b128 v[212:215], v171 offset:36864
	ds_read_b128 v[216:219], v171 offset:37888
	ds_read_b128 v[220:223], v171 offset:38912
	ds_read_b128 v[224:227], v171 offset:39936
	global_load_lds_dwordx4 v134, s[0:1]
	s_mov_b32 m0, s74
	s_nop 0
	global_load_lds_dwordx4 v138, s[0:1]
	s_waitcnt vmcnt(8)
	s_waitcnt lgkmcnt(0)
	s_barrier
	s_setprio 1
	s_waitcnt lgkmcnt(0)
	v_mfma_f32_16x16x32_bf16 v[124:127], v[128:131], v[196:199], v[124:127]
	v_mfma_f32_16x16x32_bf16 v[120:123], v[160:163], v[196:199], v[120:123]
	v_mfma_f32_16x16x32_bf16 v[108:111], v[128:131], v[204:207], v[108:111]
	v_mfma_f32_16x16x32_bf16 v[104:107], v[160:163], v[204:207], v[104:107]
	v_mfma_f32_16x16x32_bf16 v[92:95], v[128:131], v[212:215], v[92:95]
	v_mfma_f32_16x16x32_bf16 v[88:91], v[160:163], v[212:215], v[88:91]
	v_mfma_f32_16x16x32_bf16 v[76:79], v[128:131], v[220:223], v[76:79]
	v_mfma_f32_16x16x32_bf16 v[72:75], v[160:163], v[220:223], v[72:75]
	v_mfma_f32_16x16x32_bf16 v[124:127], v[156:159], v[200:203], v[124:127]
	v_mfma_f32_16x16x32_bf16 v[120:123], v[164:167], v[200:203], v[120:123]
	v_mfma_f32_16x16x32_bf16 v[108:111], v[156:159], v[208:211], v[108:111]
	v_mfma_f32_16x16x32_bf16 v[104:107], v[164:167], v[208:211], v[104:107]
	v_mfma_f32_16x16x32_bf16 v[92:95], v[156:159], v[216:219], v[92:95]
	v_mfma_f32_16x16x32_bf16 v[88:91], v[164:167], v[216:219], v[88:91]
	v_mfma_f32_16x16x32_bf16 v[76:79], v[156:159], v[224:227], v[76:79]
	v_mfma_f32_16x16x32_bf16 v[72:75], v[164:167], v[224:227], v[72:75]
	v_mfma_f32_16x16x32_bf16 v[116:119], v[176:179], v[196:199], v[116:119]
	v_mfma_f32_16x16x32_bf16 v[112:115], v[188:191], v[196:199], v[112:115]
	v_mfma_f32_16x16x32_bf16 v[100:103], v[176:179], v[204:207], v[100:103]
	v_mfma_f32_16x16x32_bf16 v[96:99], v[188:191], v[204:207], v[96:99]
	v_mfma_f32_16x16x32_bf16 v[84:87], v[176:179], v[212:215], v[84:87]
	v_mfma_f32_16x16x32_bf16 v[80:83], v[188:191], v[212:215], v[80:83]
	v_mfma_f32_16x16x32_bf16 v[68:71], v[176:179], v[220:223], v[68:71]
	v_mfma_f32_16x16x32_bf16 v[64:67], v[188:191], v[220:223], v[64:67]
	v_mfma_f32_16x16x32_bf16 v[116:119], v[180:183], v[200:203], v[116:119]
	v_mfma_f32_16x16x32_bf16 v[112:115], v[192:195], v[200:203], v[112:115]
	v_mfma_f32_16x16x32_bf16 v[100:103], v[180:183], v[208:211], v[100:103]
	v_mfma_f32_16x16x32_bf16 v[96:99], v[192:195], v[208:211], v[96:99]
	v_mfma_f32_16x16x32_bf16 v[84:87], v[180:183], v[216:219], v[84:87]
	v_mfma_f32_16x16x32_bf16 v[80:83], v[192:195], v[216:219], v[80:83]
	v_mfma_f32_16x16x32_bf16 v[68:71], v[180:183], v[224:227], v[68:71]
	v_mfma_f32_16x16x32_bf16 v[64:67], v[192:195], v[224:227], v[64:67]
	s_setprio 0
	s_barrier
	s_add_i32 s0, s83, s58
	s_mov_b32 m0, s0
	s_nop 0
	global_load_lds_dwordx4 v136, s[98:99]
	s_add_i32 m0, s0, 0x2000
	s_add_u32 s0, s6, 0x80080
	s_addc_u32 s1, s7, 0
	s_add_i32 s6, s88, s58
	global_load_lds_dwordx4 v140, s[98:99]
	s_mov_b32 m0, s6
	s_nop 0
	global_load_lds_dwordx4 v136, s[0:1]
	s_add_i32 m0, s6, 0x2000
	s_nop 0
	global_load_lds_dwordx4 v140, s[0:1]
	s_mov_b32 m0, s78
	s_nop 0
	global_load_lds_dwordx4 v134, s[100:101]
	s_mov_b32 m0, s79
	s_nop 0
	global_load_lds_dwordx4 v138, s[100:101]
	ds_read_b128 v[196:199], v171 offset:49152
	ds_read_b128 v[200:203], v171 offset:50176
	ds_read_b128 v[204:207], v171 offset:51200
	ds_read_b128 v[208:211], v171 offset:52224
	ds_read_b128 v[212:215], v171 offset:53248
	ds_read_b128 v[216:219], v171 offset:54272
	ds_read_b128 v[220:223], v171 offset:55296
	ds_read_b128 v[224:227], v171 offset:56320
	s_waitcnt vmcnt(8)
	s_waitcnt lgkmcnt(0)
	s_barrier
	s_setprio 1
	s_waitcnt lgkmcnt(0)
	v_mfma_f32_16x16x32_bf16 v[60:63], v[128:131], v[196:199], v[60:63]
	v_mfma_f32_16x16x32_bf16 v[56:59], v[160:163], v[196:199], v[56:59]
	v_mfma_f32_16x16x32_bf16 v[44:47], v[128:131], v[204:207], v[44:47]
	v_mfma_f32_16x16x32_bf16 v[40:43], v[160:163], v[204:207], v[40:43]
	v_mfma_f32_16x16x32_bf16 v[28:31], v[128:131], v[212:215], v[28:31]
	v_mfma_f32_16x16x32_bf16 v[24:27], v[160:163], v[212:215], v[24:27]
	v_mfma_f32_16x16x32_bf16 v[12:15], v[128:131], v[220:223], v[12:15]
	v_mfma_f32_16x16x32_bf16 v[8:11], v[160:163], v[220:223], v[8:11]
	v_mfma_f32_16x16x32_bf16 v[60:63], v[156:159], v[200:203], v[60:63]
	v_mfma_f32_16x16x32_bf16 v[56:59], v[164:167], v[200:203], v[56:59]
	v_mfma_f32_16x16x32_bf16 v[44:47], v[156:159], v[208:211], v[44:47]
	v_mfma_f32_16x16x32_bf16 v[40:43], v[164:167], v[208:211], v[40:43]
	v_mfma_f32_16x16x32_bf16 v[28:31], v[156:159], v[216:219], v[28:31]
	v_mfma_f32_16x16x32_bf16 v[24:27], v[164:167], v[216:219], v[24:27]
	v_mfma_f32_16x16x32_bf16 v[12:15], v[156:159], v[224:227], v[12:15]
	v_mfma_f32_16x16x32_bf16 v[8:11], v[164:167], v[224:227], v[8:11]
	v_mfma_f32_16x16x32_bf16 v[52:55], v[176:179], v[196:199], v[52:55]
	v_mfma_f32_16x16x32_bf16 v[48:51], v[188:191], v[196:199], v[48:51]
	v_mfma_f32_16x16x32_bf16 v[36:39], v[176:179], v[204:207], v[36:39]
	v_mfma_f32_16x16x32_bf16 v[32:35], v[188:191], v[204:207], v[32:35]
	v_mfma_f32_16x16x32_bf16 v[20:23], v[176:179], v[212:215], v[20:23]
	v_mfma_f32_16x16x32_bf16 v[16:19], v[188:191], v[212:215], v[16:19]
	v_mfma_f32_16x16x32_bf16 v[4:7], v[176:179], v[220:223], v[4:7]
	v_mfma_f32_16x16x32_bf16 v[0:3], v[188:191], v[220:223], v[0:3]
	v_mfma_f32_16x16x32_bf16 v[52:55], v[180:183], v[200:203], v[52:55]
	v_mfma_f32_16x16x32_bf16 v[48:51], v[192:195], v[200:203], v[48:51]
	v_mfma_f32_16x16x32_bf16 v[36:39], v[180:183], v[208:211], v[36:39]
	v_mfma_f32_16x16x32_bf16 v[32:35], v[192:195], v[208:211], v[32:35]
	v_mfma_f32_16x16x32_bf16 v[20:23], v[180:183], v[216:219], v[20:23]
	v_mfma_f32_16x16x32_bf16 v[16:19], v[192:195], v[216:219], v[16:19]
	v_mfma_f32_16x16x32_bf16 v[4:7], v[180:183], v[224:227], v[4:7]
	v_mfma_f32_16x16x32_bf16 v[0:3], v[192:195], v[224:227], v[0:3]
	s_setprio 0
	s_barrier
	s_add_i32 vcc_hi, vcc_hi, 2
	s_add_u32 s4, s4, 0x100
	s_addc_u32 s5, s5, 0
	s_add_u32 s57, s57, 0x100
	s_addc_u32 vcc_lo, vcc_lo, 0
	s_cmp_gt_u32 vcc_hi, 29
	s_cbranch_scc0 .LBB0_244
	s_and_b64 vcc, exec, s[28:29]
	s_cbranch_vccz .LBB0_247
	s_barrier

; #define PG8_STAGE(bufoff, gbase, voff) do { _Pragma("unroll") for (int _i = 0; _i < 2; ++_i) \
;         __builtin_amdgcn_global_load_lds((const unsigned*)((const char*)(gbase) + (voff)[_i]), (PG8_LAS unsigned*)(lds + (bufoff) + ldsw + _i * 8192), 16, 0, 0); } while (0)
; #define PG8_LDA(dst, b, h) do { _Pragma("unroll") for (int m = 0; m < 4; ++m) _Pragma("unroll") for (int k = 0; k < 2; ++k) dst[m][k] = *(const PG8_LAS bf16x8*)(lds + PG8_SA(b, h) + aoff + m * 2048 + k * 1024); } while (0)
; #define PG8_LDB(dst, b, h) do { _Pragma("unroll") for (int n = 0; n < 2; ++n) _Pragma("unroll") for (int k = 0; k < 2; ++k) dst[n][k] = *(const PG8_LAS bf16x8*)(lds + PG8_SB(b, h) + boff + n * 2048 + k * 1024); } while (0)
; #define PG8_MMA(ai, bj, At, Bt) do { __builtin_amdgcn_s_setprio(1); _Pragma("unroll") for (int m = 0; m < 4; ++m) _Pragma("unroll") for (int n = 0; n < 2; ++n) _Pragma("unroll") for (int k = 0; k < 2; ++k) \
;         acc[ai][bj][m][n] = __builtin_amdgcn_mfma_f32_16x16x32_bf16(Bt[n][k], At[m][k], acc[ai][bj][m][n], 0, 0, 0); __builtin_amdgcn_s_setprio(0); } while (0)
; #define PG8_WAIT_V(n) asm volatile("s_waitcnt vmcnt(" #n ")" ::: "memory")
; #define PG8_WAIT_L(n) asm volatile("s_waitcnt lgkmcnt(" #n ")" ::: "memory")
; template <class Epi, class Sched, bool ALIGN_EPI = false, bool SP2 = false>
; __device__ __forceinline__ void gemm_phase(PG8_LAS unsigned char* lds, const Gemm g, const Sched& S, const Epi& E) {
;     ...
;             const bool last = (t == nt - 2);
;             const char* a1 = cA + (size_t)(t + 1) * kstep;
;             const char* a2 = last ? nA : cA + (size_t)(t + 2) * kstep; const char* b2 = last ? nB : cB + (size_t)(t + 2) * kstep;
;             const char* a3 = a2 + kstep; const char* b3 = b2 + kstep;
;             if (last && has_next) S.a_ready(nxt);
;             if constexpr (SP2) {
;             PG8_LDB(B0, 0, 0); PG8_LDB(B1, 0, 1); PG8_SCHED; PG8_LDA(At, 0, 0); PG8_STAGE(PG8_SA(1, 1), a1 + hstep, voffA);
;             PG8_WAIT_V(8); PG8_WAIT_L(0); PG8_BAR; PG8_MMA(0, 0, At, B0); PG8_MMA(0, 1, At, B1); PG8_BAR; PG8_SCHED;
;             PG8_LDA(At, 0, 1); PG8_STAGE(PG8_SB(0, 0), b2, voffB); PG8_STAGE(PG8_SB(0, 1), b2 + hstep, voffB); PG8_STAGE(PG8_SA(0, 0), a2, voffA);
;             PG8_WAIT_V(8); PG8_WAIT_L(0); PG8_BAR; PG8_MMA(1, 0, At, B0); PG8_MMA(1, 1, At, B1); PG8_BAR; PG8_SCHED;
.LBB0_728:
	ds_read_b128 v[144:147], v151
	ds_read_b128 v[156:159], v151 offset:1024
	ds_read_b128 v[160:163], v151 offset:2048
	ds_read_b128 v[164:167], v151 offset:3072
	ds_read_b128 v[168:171], v152
	ds_read_b128 v[172:175], v152 offset:1024
	ds_read_b128 v[176:179], v152 offset:2048
	ds_read_b128 v[180:183], v152 offset:3072
	s_add_u32 s28, s26, 0xfff80080
	s_addc_u32 s29, s27, -1
	s_cmp_eq_u32 s51, 28
	s_cselect_b32 s31, s19, s29
	s_cselect_b32 s30, s47, s28
	s_cselect_b32 s29, s17, s50
	s_cselect_b32 s28, s48, s49
	s_add_i32 m0, s25, 0xc000
	ds_read_b128 v[188:191], v153
	ds_read_b128 v[192:195], v153 offset:1024
	ds_read_b128 v[196:199], v153 offset:2048
	ds_read_b128 v[200:203], v153 offset:3072
	ds_read_b128 v[204:207], v153 offset:4096
	ds_read_b128 v[208:211], v153 offset:5120
	ds_read_b128 v[212:215], v153 offset:6144
	ds_read_b128 v[216:219], v153 offset:7168
	global_load_lds_dwordx4 v136, s[26:27]
	s_add_i32 m0, s25, 0xe000
	s_nop 0
	global_load_lds_dwordx4 v138, s[26:27]
	s_waitcnt vmcnt(8)
	s_waitcnt lgkmcnt(0)
	s_barrier
	s_setprio 1
	s_waitcnt lgkmcnt(0)
	v_mfma_f32_16x16x32_bf16 v[124:127], v[144:147], v[188:191], v[124:127]
	v_mfma_f32_16x16x32_bf16 v[120:123], v[160:163], v[188:191], v[120:123]
	v_mfma_f32_16x16x32_bf16 v[108:111], v[144:147], v[196:199], v[108:111]
	v_mfma_f32_16x16x32_bf16 v[104:107], v[160:163], v[196:199], v[104:107]
	v_mfma_f32_16x16x32_bf16 v[92:95], v[144:147], v[204:207], v[92:95]
	v_mfma_f32_16x16x32_bf16 v[88:91], v[160:163], v[204:207], v[88:91]
	v_mfma_f32_16x16x32_bf16 v[76:79], v[144:147], v[212:215], v[76:79]
	v_mfma_f32_16x16x32_bf16 v[72:75], v[160:163], v[212:215], v[72:75]
	v_mfma_f32_16x16x32_bf16 v[124:127], v[156:159], v[192:195], v[124:127]
	v_mfma_f32_16x16x32_bf16 v[120:123], v[164:167], v[192:195], v[120:123]
	v_mfma_f32_16x16x32_bf16 v[108:111], v[156:159], v[200:203], v[108:111]
	v_mfma_f32_16x16x32_bf16 v[104:107], v[164:167], v[200:203], v[104:107]
	v_mfma_f32_16x16x32_bf16 v[92:95], v[156:159], v[208:211], v[92:95]
	v_mfma_f32_16x16x32_bf16 v[88:91], v[164:167], v[208:211], v[88:91]
	v_mfma_f32_16x16x32_bf16 v[76:79], v[156:159], v[216:219], v[76:79]
	v_mfma_f32_16x16x32_bf16 v[72:75], v[164:167], v[216:219], v[72:75]
	v_mfma_f32_16x16x32_bf16 v[116:119], v[168:171], v[188:191], v[116:119]
	v_mfma_f32_16x16x32_bf16 v[112:115], v[176:179], v[188:191], v[112:115]
	v_mfma_f32_16x16x32_bf16 v[100:103], v[168:171], v[196:199], v[100:103]
	v_mfma_f32_16x16x32_bf16 v[96:99], v[176:179], v[196:199], v[96:99]
	v_mfma_f32_16x16x32_bf16 v[84:87], v[168:171], v[204:207], v[84:87]
	v_mfma_f32_16x16x32_bf16 v[80:83], v[176:179], v[204:207], v[80:83]
	v_mfma_f32_16x16x32_bf16 v[68:71], v[168:171], v[212:215], v[68:71]
	v_mfma_f32_16x16x32_bf16 v[64:67], v[176:179], v[212:215], v[64:67]
	v_mfma_f32_16x16x32_bf16 v[116:119], v[172:175], v[192:195], v[116:119]
	v_mfma_f32_16x16x32_bf16 v[112:115], v[180:183], v[192:195], v[112:115]
	v_mfma_f32_16x16x32_bf16 v[100:103], v[172:175], v[200:203], v[100:103]
	v_mfma_f32_16x16x32_bf16 v[96:99], v[180:183], v[200:203], v[96:99]
	v_mfma_f32_16x16x32_bf16 v[84:87], v[172:175], v[208:211], v[84:87]
	v_mfma_f32_16x16x32_bf16 v[80:83], v[180:183], v[208:211], v[80:83]
	v_mfma_f32_16x16x32_bf16 v[68:71], v[172:175], v[216:219], v[68:71]
	v_mfma_f32_16x16x32_bf16 v[64:67], v[180:183], v[216:219], v[64:67]
	s_setprio 0
	s_barrier
	s_add_u32 s98, s28, s12
	s_addc_u32 s99, s29, s13
	s_add_u32 s100, s30, s12
	s_addc_u32 s101, s31, s13
	s_add_i32 s54, s43, s1
	s_mov_b32 m0, s54
	s_nop 0
	global_load_lds_dwordx4 v130, s[28:29]
	s_add_i32 m0, s54, 0x2000
	s_add_u32 s54, s28, 0x80000
	s_addc_u32 s55, s29, 0
	s_add_i32 s56, s44, s1
	global_load_lds_dwordx4 v134, s[28:29]
	s_mov_b32 m0, s56
	s_nop 0
	global_load_lds_dwordx4 v130, s[54:55]
	s_add_i32 m0, s56, 0x2000
	s_nop 0
	global_load_lds_dwordx4 v134, s[54:55]
	s_mov_b32 m0, s25
	s_nop 0
	global_load_lds_dwordx4 v128, s[30:31]
	s_mov_b32 m0, s34
	s_nop 0
	global_load_lds_dwordx4 v132, s[30:31]
	ds_read_b128 v[188:191], v153 offset:16384
	ds_read_b128 v[192:195], v153 offset:17408
	ds_read_b128 v[196:199], v153 offset:18432
	ds_read_b128 v[200:203], v153 offset:19456
	ds_read_b128 v[204:207], v153 offset:20480
	ds_read_b128 v[208:211], v153 offset:21504
	ds_read_b128 v[212:215], v153 offset:22528
	ds_read_b128 v[216:219], v153 offset:23552
	s_waitcnt vmcnt(8)
	s_waitcnt lgkmcnt(0)
	s_barrier
	s_setprio 1
	s_waitcnt lgkmcnt(0)
	v_mfma_f32_16x16x32_bf16 v[60:63], v[144:147], v[188:191], v[60:63]
	v_mfma_f32_16x16x32_bf16 v[56:59], v[160:163], v[188:191], v[56:59]
	v_mfma_f32_16x16x32_bf16 v[44:47], v[144:147], v[196:199], v[44:47]
	v_mfma_f32_16x16x32_bf16 v[40:43], v[160:163], v[196:199], v[40:43]
	v_mfma_f32_16x16x32_bf16 v[28:31], v[144:147], v[204:207], v[28:31]
	v_mfma_f32_16x16x32_bf16 v[24:27], v[160:163], v[204:207], v[24:27]
	v_mfma_f32_16x16x32_bf16 v[12:15], v[144:147], v[212:215], v[12:15]
	v_mfma_f32_16x16x32_bf16 v[8:11], v[160:163], v[212:215], v[8:11]
	v_mfma_f32_16x16x32_bf16 v[60:63], v[156:159], v[192:195], v[60:63]
	v_mfma_f32_16x16x32_bf16 v[56:59], v[164:167], v[192:195], v[56:59]
	v_mfma_f32_16x16x32_bf16 v[44:47], v[156:159], v[200:203], v[44:47]
	v_mfma_f32_16x16x32_bf16 v[40:43], v[164:167], v[200:203], v[40:43]
	v_mfma_f32_16x16x32_bf16 v[28:31], v[156:159], v[208:211], v[28:31]
	v_mfma_f32_16x16x32_bf16 v[24:27], v[164:167], v[208:211], v[24:27]
	v_mfma_f32_16x16x32_bf16 v[12:15], v[156:159], v[216:219], v[12:15]
	v_mfma_f32_16x16x32_bf16 v[8:11], v[164:167], v[216:219], v[8:11]
	v_mfma_f32_16x16x32_bf16 v[52:55], v[168:171], v[188:191], v[52:55]
	v_mfma_f32_16x16x32_bf16 v[48:51], v[176:179], v[188:191], v[48:51]
	v_mfma_f32_16x16x32_bf16 v[36:39], v[168:171], v[196:199], v[36:39]
	v_mfma_f32_16x16x32_bf16 v[32:35], v[176:179], v[196:199], v[32:35]
	v_mfma_f32_16x16x32_bf16 v[20:23], v[168:171], v[204:207], v[20:23]
	v_mfma_f32_16x16x32_bf16 v[16:19], v[176:179], v[204:207], v[16:19]
	v_mfma_f32_16x16x32_bf16 v[4:7], v[168:171], v[212:215], v[4:7]
	v_mfma_f32_16x16x32_bf16 v[0:3], v[176:179], v[212:215], v[0:3]
	v_mfma_f32_16x16x32_bf16 v[52:55], v[172:175], v[192:195], v[52:55]
	v_mfma_f32_16x16x32_bf16 v[48:51], v[180:183], v[192:195], v[48:51]
	v_mfma_f32_16x16x32_bf16 v[36:39], v[172:175], v[200:203], v[36:39]
	v_mfma_f32_16x16x32_bf16 v[32:35], v[180:183], v[200:203], v[32:35]
	v_mfma_f32_16x16x32_bf16 v[20:23], v[172:175], v[208:211], v[20:23]
	v_mfma_f32_16x16x32_bf16 v[16:19], v[180:183], v[208:211], v[16:19]
	v_mfma_f32_16x16x32_bf16 v[4:7], v[172:175], v[216:219], v[4:7]
	v_mfma_f32_16x16x32_bf16 v[0:3], v[180:183], v[216:219], v[0:3]
	s_setprio 0
	s_barrier
; #define PG8_STAGE(bufoff, gbase, voff) do { _Pragma("unroll") for (int _i = 0; _i < 2; ++_i) \
;         __builtin_amdgcn_global_load_lds((const unsigned*)((const char*)(gbase) + (voff)[_i]), (PG8_LAS unsigned*)(lds + (bufoff) + ldsw + _i * 8192), 16, 0, 0); } while (0)
; #define PG8_LDA(dst, b, h) do { _Pragma("unroll") for (int m = 0; m < 4; ++m) _Pragma("unroll") for (int k = 0; k < 2; ++k) dst[m][k] = *(const PG8_LAS bf16x8*)(lds + PG8_SA(b, h) + aoff + m * 2048 + k * 1024); } while (0)
; #define PG8_LDB(dst, b, h) do { _Pragma("unroll") for (int n = 0; n < 2; ++n) _Pragma("unroll") for (int k = 0; k < 2; ++k) dst[n][k] = *(const PG8_LAS bf16x8*)(lds + PG8_SB(b, h) + boff + n * 2048 + k * 1024); } while (0)
; #define PG8_MMA(ai, bj, At, Bt) do { __builtin_amdgcn_s_setprio(1); _Pragma("unroll") for (int m = 0; m < 4; ++m) _Pragma("unroll") for (int n = 0; n < 2; ++n) _Pragma("unroll") for (int k = 0; k < 2; ++k) \
;         acc[ai][bj][m][n] = __builtin_amdgcn_mfma_f32_16x16x32_bf16(Bt[n][k], At[m][k], acc[ai][bj][m][n], 0, 0, 0); __builtin_amdgcn_s_setprio(0); } while (0)
; #define PG8_WAIT_V(n) asm volatile("s_waitcnt vmcnt(" #n ")" ::: "memory")
; #define PG8_WAIT_L(n) asm volatile("s_waitcnt lgkmcnt(" #n ")" ::: "memory")
; #define PG8_BAR __builtin_amdgcn_s_barrier()
; #define PG8_SCHED __builtin_amdgcn_sched_barrier(0)
; template <class Epi, class Sched, bool ALIGN_EPI = false, bool SP2 = false>
; __device__ __forceinline__ void gemm_phase(PG8_LAS unsigned char* lds, const Gemm g, const Sched& S, const Epi& E) {
;     ...
;             PG8_LDB(B0, 1, 0); PG8_LDB(B1, 1, 1); PG8_SCHED; PG8_LDA(At, 1, 0); PG8_STAGE(PG8_SA(0, 1), a2 + hstep, voffA);
;             PG8_WAIT_V(8); PG8_WAIT_L(0); PG8_BAR; PG8_MMA(0, 0, At, B0); PG8_MMA(0, 1, At, B1); PG8_BAR; PG8_SCHED;
;             PG8_LDA(At, 1, 1); PG8_STAGE(PG8_SB(1, 0), b3, voffB); PG8_STAGE(PG8_SB(1, 1), b3 + hstep, voffB); PG8_STAGE(PG8_SA(1, 0), a3, voffA);
;             PG8_WAIT_V(8); PG8_WAIT_L(0); PG8_BAR; PG8_MMA(1, 0, At, B0); PG8_MMA(1, 1, At, B1); PG8_BAR; PG8_SCHED;
	s_add_i32 s54, 0, 0x18000
	v_add_u32_e32 v155, s54, v150
	s_add_i32 s55, 0, 0x1c000
	ds_read_b128 v[144:147], v155
	ds_read_b128 v[156:159], v155 offset:1024
	ds_read_b128 v[160:163], v155 offset:2048
	ds_read_b128 v[164:167], v155 offset:3072
	v_add_u32_e32 v155, s55, v150
	ds_read_b128 v[168:171], v155
	ds_read_b128 v[172:175], v155 offset:1024
	ds_read_b128 v[176:179], v155 offset:2048
	ds_read_b128 v[180:183], v155 offset:3072
	s_add_u32 s30, s30, 0x80000
	s_addc_u32 s31, s31, 0
	s_mov_b32 m0, s35
	ds_read_b128 v[188:191], v153 offset:32768
	ds_read_b128 v[192:195], v153 offset:33792
	ds_read_b128 v[196:199], v153 offset:34816
	ds_read_b128 v[200:203], v153 offset:35840
	ds_read_b128 v[204:207], v153 offset:36864
	ds_read_b128 v[208:211], v153 offset:37888
	ds_read_b128 v[212:215], v153 offset:38912
	ds_read_b128 v[216:219], v153 offset:39936
	global_load_lds_dwordx4 v128, s[30:31]
	s_mov_b32 m0, s36
	s_nop 0
	global_load_lds_dwordx4 v132, s[30:31]
	s_waitcnt vmcnt(8)
	s_waitcnt lgkmcnt(0)
	s_barrier
	s_setprio 1
	s_waitcnt lgkmcnt(0)
	v_mfma_f32_16x16x32_bf16 v[124:127], v[144:147], v[188:191], v[124:127]
	v_mfma_f32_16x16x32_bf16 v[120:123], v[160:163], v[188:191], v[120:123]
	v_mfma_f32_16x16x32_bf16 v[108:111], v[144:147], v[196:199], v[108:111]
	v_mfma_f32_16x16x32_bf16 v[104:107], v[160:163], v[196:199], v[104:107]
	v_mfma_f32_16x16x32_bf16 v[92:95], v[144:147], v[204:207], v[92:95]
	v_mfma_f32_16x16x32_bf16 v[88:91], v[160:163], v[204:207], v[88:91]
	v_mfma_f32_16x16x32_bf16 v[76:79], v[144:147], v[212:215], v[76:79]
	v_mfma_f32_16x16x32_bf16 v[72:75], v[160:163], v[212:215], v[72:75]
	v_mfma_f32_16x16x32_bf16 v[124:127], v[156:159], v[192:195], v[124:127]
	v_mfma_f32_16x16x32_bf16 v[120:123], v[164:167], v[192:195], v[120:123]
	v_mfma_f32_16x16x32_bf16 v[108:111], v[156:159], v[200:203], v[108:111]
	v_mfma_f32_16x16x32_bf16 v[104:107], v[164:167], v[200:203], v[104:107]
	v_mfma_f32_16x16x32_bf16 v[92:95], v[156:159], v[208:211], v[92:95]
	v_mfma_f32_16x16x32_bf16 v[88:91], v[164:167], v[208:211], v[88:91]
	v_mfma_f32_16x16x32_bf16 v[76:79], v[156:159], v[216:219], v[76:79]
	v_mfma_f32_16x16x32_bf16 v[72:75], v[164:167], v[216:219], v[72:75]
	v_mfma_f32_16x16x32_bf16 v[116:119], v[168:171], v[188:191], v[116:119]
	v_mfma_f32_16x16x32_bf16 v[112:115], v[176:179], v[188:191], v[112:115]
	v_mfma_f32_16x16x32_bf16 v[100:103], v[168:171], v[196:199], v[100:103]
	v_mfma_f32_16x16x32_bf16 v[96:99], v[176:179], v[196:199], v[96:99]
	v_mfma_f32_16x16x32_bf16 v[84:87], v[168:171], v[204:207], v[84:87]
	v_mfma_f32_16x16x32_bf16 v[80:83], v[176:179], v[204:207], v[80:83]
	v_mfma_f32_16x16x32_bf16 v[68:71], v[168:171], v[212:215], v[68:71]
	v_mfma_f32_16x16x32_bf16 v[64:67], v[176:179], v[212:215], v[64:67]
	v_mfma_f32_16x16x32_bf16 v[116:119], v[172:175], v[192:195], v[116:119]
	v_mfma_f32_16x16x32_bf16 v[112:115], v[180:183], v[192:195], v[112:115]
	v_mfma_f32_16x16x32_bf16 v[100:103], v[172:175], v[200:203], v[100:103]
	v_mfma_f32_16x16x32_bf16 v[96:99], v[180:183], v[200:203], v[96:99]
	v_mfma_f32_16x16x32_bf16 v[84:87], v[172:175], v[208:211], v[84:87]
	v_mfma_f32_16x16x32_bf16 v[80:83], v[180:183], v[208:211], v[80:83]
	v_mfma_f32_16x16x32_bf16 v[68:71], v[172:175], v[216:219], v[68:71]
	v_mfma_f32_16x16x32_bf16 v[64:67], v[180:183], v[216:219], v[64:67]
	s_setprio 0
	s_barrier
	s_add_i32 s30, s54, s1
	s_mov_b32 m0, s30
	s_nop 0
	global_load_lds_dwordx4 v130, s[98:99]
	s_add_i32 m0, s30, 0x2000
	s_add_u32 s28, s28, 0x80080
	s_addc_u32 s29, s29, 0
	s_add_i32 s30, s55, s1
	global_load_lds_dwordx4 v134, s[98:99]
	s_mov_b32 m0, s30
	s_nop 0
	global_load_lds_dwordx4 v130, s[28:29]
	s_add_i32 m0, s30, 0x2000
	s_nop 0
	global_load_lds_dwordx4 v134, s[28:29]
	s_mov_b32 m0, s40
	s_nop 0
	global_load_lds_dwordx4 v128, s[100:101]
	s_mov_b32 m0, s41
	s_nop 0
	global_load_lds_dwordx4 v132, s[100:101]
	ds_read_b128 v[188:191], v153 offset:49152
	ds_read_b128 v[192:195], v153 offset:50176
	ds_read_b128 v[196:199], v153 offset:51200
	ds_read_b128 v[200:203], v153 offset:52224
	ds_read_b128 v[204:207], v153 offset:53248
	ds_read_b128 v[208:211], v153 offset:54272
	ds_read_b128 v[212:215], v153 offset:55296
	ds_read_b128 v[216:219], v153 offset:56320
	s_waitcnt vmcnt(8)
	s_waitcnt lgkmcnt(0)
	s_barrier
	s_setprio 1
	s_waitcnt lgkmcnt(0)
	v_mfma_f32_16x16x32_bf16 v[60:63], v[144:147], v[188:191], v[60:63]
	v_mfma_f32_16x16x32_bf16 v[56:59], v[160:163], v[188:191], v[56:59]
	v_mfma_f32_16x16x32_bf16 v[44:47], v[144:147], v[196:199], v[44:47]
	v_mfma_f32_16x16x32_bf16 v[40:43], v[160:163], v[196:199], v[40:43]
	v_mfma_f32_16x16x32_bf16 v[28:31], v[144:147], v[204:207], v[28:31]
	v_mfma_f32_16x16x32_bf16 v[24:27], v[160:163], v[204:207], v[24:27]
	v_mfma_f32_16x16x32_bf16 v[12:15], v[144:147], v[212:215], v[12:15]
	v_mfma_f32_16x16x32_bf16 v[8:11], v[160:163], v[212:215], v[8:11]
	v_mfma_f32_16x16x32_bf16 v[60:63], v[156:159], v[192:195], v[60:63]
	v_mfma_f32_16x16x32_bf16 v[56:59], v[164:167], v[192:195], v[56:59]
	v_mfma_f32_16x16x32_bf16 v[44:47], v[156:159], v[200:203], v[44:47]
	v_mfma_f32_16x16x32_bf16 v[40:43], v[164:167], v[200:203], v[40:43]
	v_mfma_f32_16x16x32_bf16 v[28:31], v[156:159], v[208:211], v[28:31]
	v_mfma_f32_16x16x32_bf16 v[24:27], v[164:167], v[208:211], v[24:27]
	v_mfma_f32_16x16x32_bf16 v[12:15], v[156:159], v[216:219], v[12:15]
	v_mfma_f32_16x16x32_bf16 v[8:11], v[164:167], v[216:219], v[8:11]
	v_mfma_f32_16x16x32_bf16 v[52:55], v[168:171], v[188:191], v[52:55]
	v_mfma_f32_16x16x32_bf16 v[48:51], v[176:179], v[188:191], v[48:51]
	v_mfma_f32_16x16x32_bf16 v[36:39], v[168:171], v[196:199], v[36:39]
	v_mfma_f32_16x16x32_bf16 v[32:35], v[176:179], v[196:199], v[32:35]
	v_mfma_f32_16x16x32_bf16 v[20:23], v[168:171], v[204:207], v[20:23]
	v_mfma_f32_16x16x32_bf16 v[16:19], v[176:179], v[204:207], v[16:19]
	v_mfma_f32_16x16x32_bf16 v[4:7], v[168:171], v[212:215], v[4:7]
	v_mfma_f32_16x16x32_bf16 v[0:3], v[176:179], v[212:215], v[0:3]
	v_mfma_f32_16x16x32_bf16 v[52:55], v[172:175], v[192:195], v[52:55]
	v_mfma_f32_16x16x32_bf16 v[48:51], v[180:183], v[192:195], v[48:51]
	v_mfma_f32_16x16x32_bf16 v[36:39], v[172:175], v[200:203], v[36:39]
	v_mfma_f32_16x16x32_bf16 v[32:35], v[180:183], v[200:203], v[32:35]
	v_mfma_f32_16x16x32_bf16 v[20:23], v[172:175], v[208:211], v[20:23]
	v_mfma_f32_16x16x32_bf16 v[16:19], v[180:183], v[208:211], v[16:19]
	v_mfma_f32_16x16x32_bf16 v[4:7], v[172:175], v[216:219], v[4:7]
	v_mfma_f32_16x16x32_bf16 v[0:3], v[180:183], v[216:219], v[0:3]
	s_setprio 0
	s_barrier
	s_add_i32 s51, s51, 2
	s_add_u32 s26, s26, 0x100
	s_addc_u32 s27, s27, 0
	s_add_u32 s49, s49, 0x100
	s_addc_u32 s50, s50, 0
	s_cmp_gt_u32 s51, 29
	s_cbranch_scc0 .LBB0_728
	s_and_b64 vcc, exec, s[14:15]
	s_cbranch_vccz .LBB0_731
	s_barrier

; #define PG8_STAGE(bufoff, gbase, voff) do { _Pragma("unroll") for (int _i = 0; _i < 2; ++_i) \
;         __builtin_amdgcn_global_load_lds((const unsigned*)((const char*)(gbase) + (voff)[_i]), (PG8_LAS unsigned*)(lds + (bufoff) + ldsw + _i * 8192), 16, 0, 0); } while (0)
; #define PG8_LDA(dst, b, h) do { _Pragma("unroll") for (int m = 0; m < 4; ++m) _Pragma("unroll") for (int k = 0; k < 2; ++k) dst[m][k] = *(const PG8_LAS bf16x8*)(lds + PG8_SA(b, h) + aoff + m * 2048 + k * 1024); } while (0)
; #define PG8_LDB(dst, b, h) do { _Pragma("unroll") for (int n = 0; n < 2; ++n) _Pragma("unroll") for (int k = 0; k < 2; ++k) dst[n][k] = *(const PG8_LAS bf16x8*)(lds + PG8_SB(b, h) + boff + n * 2048 + k * 1024); } while (0)
; #define PG8_MMA(ai, bj, At, Bt) do { __builtin_amdgcn_s_setprio(1); _Pragma("unroll") for (int m = 0; m < 4; ++m) _Pragma("unroll") for (int n = 0; n < 2; ++n) _Pragma("unroll") for (int k = 0; k < 2; ++k) \
;         acc[ai][bj][m][n] = __builtin_amdgcn_mfma_f32_16x16x32_bf16(Bt[n][k], At[m][k], acc[ai][bj][m][n], 0, 0, 0); __builtin_amdgcn_s_setprio(0); } while (0)
; #define PG8_WAIT_V(n) asm volatile("s_waitcnt vmcnt(" #n ")" ::: "memory")
; #define PG8_WAIT_L(n) asm volatile("s_waitcnt lgkmcnt(" #n ")" ::: "memory")
; template <class Epi, class Sched, bool ALIGN_EPI = false, bool SP2 = false>
; __device__ __forceinline__ void gemm_phase(PG8_LAS unsigned char* lds, const Gemm g, const Sched& S, const Epi& E) {
;     ...
;             const bool last = (t == nt - 2);
;             const char* a1 = cA + (size_t)(t + 1) * kstep;
;             const char* a2 = last ? nA : cA + (size_t)(t + 2) * kstep; const char* b2 = last ? nB : cB + (size_t)(t + 2) * kstep;
;             const char* a3 = a2 + kstep; const char* b3 = b2 + kstep;
;             if (last && has_next) S.a_ready(nxt);
;             if constexpr (SP2) {
;             PG8_LDB(B0, 0, 0); PG8_LDB(B1, 0, 1); PG8_SCHED; PG8_LDA(At, 0, 0); PG8_STAGE(PG8_SA(1, 1), a1 + hstep, voffA);
;             PG8_WAIT_V(8); PG8_WAIT_L(0); PG8_BAR; PG8_MMA(0, 0, At, B0); PG8_MMA(0, 1, At, B1); PG8_BAR; PG8_SCHED;
;             PG8_LDA(At, 0, 1); PG8_STAGE(PG8_SB(0, 0), b2, voffB); PG8_STAGE(PG8_SB(0, 1), b2 + hstep, voffB); PG8_STAGE(PG8_SA(0, 0), a2, voffA);
;             PG8_WAIT_V(8); PG8_WAIT_L(0); PG8_BAR; PG8_MMA(1, 0, At, B0); PG8_MMA(1, 1, At, B1); PG8_BAR; PG8_SCHED;
.LBB0_803:
	ds_read_b128 v[144:147], v151
	ds_read_b128 v[154:157], v151 offset:1024
	ds_read_b128 v[158:161], v151 offset:2048
	ds_read_b128 v[162:165], v151 offset:3072
	ds_read_b128 v[166:169], v152
	ds_read_b128 v[170:173], v152 offset:1024
	ds_read_b128 v[174:177], v152 offset:2048
	ds_read_b128 v[178:181], v152 offset:3072
	s_add_u32 s30, s28, 0xffe00080
	s_addc_u32 s31, s29, -1
	s_cmpk_eq_i32 s51, 0x7c
	s_cselect_b32 s35, s21, s31
	s_cselect_b32 s34, s47, s30
	s_cselect_b32 s31, s19, s50
	s_cselect_b32 s30, s48, s49
	s_add_i32 m0, s27, 0xc000
	ds_read_b128 v[182:185], v153
	ds_read_b128 v[188:191], v153 offset:1024
	ds_read_b128 v[192:195], v153 offset:2048
	ds_read_b128 v[196:199], v153 offset:3072
	ds_read_b128 v[200:203], v153 offset:4096
	ds_read_b128 v[204:207], v153 offset:5120
	ds_read_b128 v[208:211], v153 offset:6144
	ds_read_b128 v[212:215], v153 offset:7168
	global_load_lds_dwordx4 v136, s[28:29]
	s_add_i32 m0, s27, 0xe000
	s_nop 0
	global_load_lds_dwordx4 v138, s[28:29]
	s_waitcnt vmcnt(8)
	s_waitcnt lgkmcnt(0)
	s_barrier
	s_setprio 1
	s_waitcnt lgkmcnt(0)
	v_mfma_f32_16x16x32_bf16 v[124:127], v[144:147], v[182:185], v[124:127]
	v_mfma_f32_16x16x32_bf16 v[120:123], v[158:161], v[182:185], v[120:123]
	v_mfma_f32_16x16x32_bf16 v[112:115], v[144:147], v[192:195], v[112:115]
	v_mfma_f32_16x16x32_bf16 v[104:107], v[158:161], v[192:195], v[104:107]
	v_mfma_f32_16x16x32_bf16 v[96:99], v[144:147], v[200:203], v[96:99]
	v_mfma_f32_16x16x32_bf16 v[88:91], v[158:161], v[200:203], v[88:91]
	v_mfma_f32_16x16x32_bf16 v[80:83], v[144:147], v[208:211], v[80:83]
	v_mfma_f32_16x16x32_bf16 v[72:75], v[158:161], v[208:211], v[72:75]
	v_mfma_f32_16x16x32_bf16 v[124:127], v[154:157], v[188:191], v[124:127]
	v_mfma_f32_16x16x32_bf16 v[120:123], v[162:165], v[188:191], v[120:123]
	v_mfma_f32_16x16x32_bf16 v[112:115], v[154:157], v[196:199], v[112:115]
	v_mfma_f32_16x16x32_bf16 v[104:107], v[162:165], v[196:199], v[104:107]
	v_mfma_f32_16x16x32_bf16 v[96:99], v[154:157], v[204:207], v[96:99]
	v_mfma_f32_16x16x32_bf16 v[88:91], v[162:165], v[204:207], v[88:91]
	v_mfma_f32_16x16x32_bf16 v[80:83], v[154:157], v[212:215], v[80:83]
	v_mfma_f32_16x16x32_bf16 v[72:75], v[162:165], v[212:215], v[72:75]
	v_mfma_f32_16x16x32_bf16 v[116:119], v[166:169], v[182:185], v[116:119]
	v_mfma_f32_16x16x32_bf16 v[108:111], v[174:177], v[182:185], v[108:111]
	v_mfma_f32_16x16x32_bf16 v[100:103], v[166:169], v[192:195], v[100:103]
	v_mfma_f32_16x16x32_bf16 v[92:95], v[174:177], v[192:195], v[92:95]
	v_mfma_f32_16x16x32_bf16 v[84:87], v[166:169], v[200:203], v[84:87]
	v_mfma_f32_16x16x32_bf16 v[76:79], v[174:177], v[200:203], v[76:79]
	v_mfma_f32_16x16x32_bf16 v[68:71], v[166:169], v[208:211], v[68:71]
	v_mfma_f32_16x16x32_bf16 v[64:67], v[174:177], v[208:211], v[64:67]
	v_mfma_f32_16x16x32_bf16 v[116:119], v[170:173], v[188:191], v[116:119]
	v_mfma_f32_16x16x32_bf16 v[108:111], v[178:181], v[188:191], v[108:111]
	v_mfma_f32_16x16x32_bf16 v[100:103], v[170:173], v[196:199], v[100:103]
	v_mfma_f32_16x16x32_bf16 v[92:95], v[178:181], v[196:199], v[92:95]
	v_mfma_f32_16x16x32_bf16 v[84:87], v[170:173], v[204:207], v[84:87]
	v_mfma_f32_16x16x32_bf16 v[76:79], v[178:181], v[204:207], v[76:79]
	v_mfma_f32_16x16x32_bf16 v[68:71], v[170:173], v[212:215], v[68:71]
	v_mfma_f32_16x16x32_bf16 v[64:67], v[178:181], v[212:215], v[64:67]
	s_setprio 0
	s_barrier
	s_add_u32 s98, s30, s14
	s_addc_u32 s99, s31, s15
	s_add_u32 s100, s34, s14
	s_addc_u32 s101, s35, s15
	s_add_i32 s54, s43, s1
	s_mov_b32 m0, s54
	s_nop 0
	global_load_lds_dwordx4 v130, s[30:31]
	s_add_i32 m0, s54, 0x2000
	s_add_u32 s54, s30, 0x200000
	s_addc_u32 s55, s31, 0
	s_add_i32 s56, s44, s1
	global_load_lds_dwordx4 v134, s[30:31]
	s_mov_b32 m0, s56
	s_nop 0
	global_load_lds_dwordx4 v130, s[54:55]
	s_add_i32 m0, s56, 0x2000
	s_nop 0
	global_load_lds_dwordx4 v134, s[54:55]
	s_mov_b32 m0, s27
	s_nop 0
	global_load_lds_dwordx4 v128, s[34:35]
	s_mov_b32 m0, s36
	s_nop 0
	global_load_lds_dwordx4 v132, s[34:35]
	ds_read_b128 v[182:185], v153 offset:16384
	ds_read_b128 v[188:191], v153 offset:17408
	ds_read_b128 v[192:195], v153 offset:18432
	ds_read_b128 v[196:199], v153 offset:19456
	ds_read_b128 v[200:203], v153 offset:20480
	ds_read_b128 v[204:207], v153 offset:21504
	ds_read_b128 v[208:211], v153 offset:22528
	ds_read_b128 v[212:215], v153 offset:23552
	s_waitcnt vmcnt(8)
	s_waitcnt lgkmcnt(0)
	s_barrier
	s_setprio 1
	s_waitcnt lgkmcnt(0)
	v_mfma_f32_16x16x32_bf16 v[60:63], v[144:147], v[182:185], v[60:63]
	v_mfma_f32_16x16x32_bf16 v[56:59], v[158:161], v[182:185], v[56:59]
	v_mfma_f32_16x16x32_bf16 v[48:51], v[144:147], v[192:195], v[48:51]
	v_mfma_f32_16x16x32_bf16 v[40:43], v[158:161], v[192:195], v[40:43]
	v_mfma_f32_16x16x32_bf16 v[32:35], v[144:147], v[200:203], v[32:35]
	v_mfma_f32_16x16x32_bf16 v[24:27], v[158:161], v[200:203], v[24:27]
	v_mfma_f32_16x16x32_bf16 v[16:19], v[144:147], v[208:211], v[16:19]
	v_mfma_f32_16x16x32_bf16 v[8:11], v[158:161], v[208:211], v[8:11]
	v_mfma_f32_16x16x32_bf16 v[60:63], v[154:157], v[188:191], v[60:63]
	v_mfma_f32_16x16x32_bf16 v[56:59], v[162:165], v[188:191], v[56:59]
	v_mfma_f32_16x16x32_bf16 v[48:51], v[154:157], v[196:199], v[48:51]
	v_mfma_f32_16x16x32_bf16 v[40:43], v[162:165], v[196:199], v[40:43]
	v_mfma_f32_16x16x32_bf16 v[32:35], v[154:157], v[204:207], v[32:35]
	v_mfma_f32_16x16x32_bf16 v[24:27], v[162:165], v[204:207], v[24:27]
	v_mfma_f32_16x16x32_bf16 v[16:19], v[154:157], v[212:215], v[16:19]
	v_mfma_f32_16x16x32_bf16 v[8:11], v[162:165], v[212:215], v[8:11]
	v_mfma_f32_16x16x32_bf16 v[52:55], v[166:169], v[182:185], v[52:55]
	v_mfma_f32_16x16x32_bf16 v[44:47], v[174:177], v[182:185], v[44:47]
	v_mfma_f32_16x16x32_bf16 v[36:39], v[166:169], v[192:195], v[36:39]
	v_mfma_f32_16x16x32_bf16 v[28:31], v[174:177], v[192:195], v[28:31]
	v_mfma_f32_16x16x32_bf16 v[20:23], v[166:169], v[200:203], v[20:23]
	v_mfma_f32_16x16x32_bf16 v[12:15], v[174:177], v[200:203], v[12:15]
	v_mfma_f32_16x16x32_bf16 v[4:7], v[166:169], v[208:211], v[4:7]
	v_mfma_f32_16x16x32_bf16 v[0:3], v[174:177], v[208:211], v[0:3]
	v_mfma_f32_16x16x32_bf16 v[52:55], v[170:173], v[188:191], v[52:55]
	v_mfma_f32_16x16x32_bf16 v[44:47], v[178:181], v[188:191], v[44:47]
	v_mfma_f32_16x16x32_bf16 v[36:39], v[170:173], v[196:199], v[36:39]
	v_mfma_f32_16x16x32_bf16 v[28:31], v[178:181], v[196:199], v[28:31]
	v_mfma_f32_16x16x32_bf16 v[20:23], v[170:173], v[204:207], v[20:23]
	v_mfma_f32_16x16x32_bf16 v[12:15], v[178:181], v[204:207], v[12:15]
	v_mfma_f32_16x16x32_bf16 v[4:7], v[170:173], v[212:215], v[4:7]
	v_mfma_f32_16x16x32_bf16 v[0:3], v[178:181], v[212:215], v[0:3]
	s_setprio 0
	s_barrier
; #define PG8_STAGE(bufoff, gbase, voff) do { _Pragma("unroll") for (int _i = 0; _i < 2; ++_i) \
;         __builtin_amdgcn_global_load_lds((const unsigned*)((const char*)(gbase) + (voff)[_i]), (PG8_LAS unsigned*)(lds + (bufoff) + ldsw + _i * 8192), 16, 0, 0); } while (0)
; #define PG8_LDA(dst, b, h) do { _Pragma("unroll") for (int m = 0; m < 4; ++m) _Pragma("unroll") for (int k = 0; k < 2; ++k) dst[m][k] = *(const PG8_LAS bf16x8*)(lds + PG8_SA(b, h) + aoff + m * 2048 + k * 1024); } while (0)
; #define PG8_LDB(dst, b, h) do { _Pragma("unroll") for (int n = 0; n < 2; ++n) _Pragma("unroll") for (int k = 0; k < 2; ++k) dst[n][k] = *(const PG8_LAS bf16x8*)(lds + PG8_SB(b, h) + boff + n * 2048 + k * 1024); } while (0)
; #define PG8_MMA(ai, bj, At, Bt) do { __builtin_amdgcn_s_setprio(1); _Pragma("unroll") for (int m = 0; m < 4; ++m) _Pragma("unroll") for (int n = 0; n < 2; ++n) _Pragma("unroll") for (int k = 0; k < 2; ++k) \
;         acc[ai][bj][m][n] = __builtin_amdgcn_mfma_f32_16x16x32_bf16(Bt[n][k], At[m][k], acc[ai][bj][m][n], 0, 0, 0); __builtin_amdgcn_s_setprio(0); } while (0)
; #define PG8_WAIT_V(n) asm volatile("s_waitcnt vmcnt(" #n ")" ::: "memory")
; #define PG8_WAIT_L(n) asm volatile("s_waitcnt lgkmcnt(" #n ")" ::: "memory")
; #define PG8_BAR __builtin_amdgcn_s_barrier()
; #define PG8_SCHED __builtin_amdgcn_sched_barrier(0)
; template <class Epi, class Sched, bool ALIGN_EPI = false, bool SP2 = false>
; __device__ __forceinline__ void gemm_phase(PG8_LAS unsigned char* lds, const Gemm g, const Sched& S, const Epi& E) {
;     ...
;             PG8_LDB(B0, 1, 0); PG8_LDB(B1, 1, 1); PG8_SCHED; PG8_LDA(At, 1, 0); PG8_STAGE(PG8_SA(0, 1), a2 + hstep, voffA);
;             PG8_WAIT_V(8); PG8_WAIT_L(0); PG8_BAR; PG8_MMA(0, 0, At, B0); PG8_MMA(0, 1, At, B1); PG8_BAR; PG8_SCHED;
;             PG8_LDA(At, 1, 1); PG8_STAGE(PG8_SB(1, 0), b3, voffB); PG8_STAGE(PG8_SB(1, 1), b3 + hstep, voffB); PG8_STAGE(PG8_SA(1, 0), a3, voffA);
;             PG8_WAIT_V(8); PG8_WAIT_L(0); PG8_BAR; PG8_MMA(1, 0, At, B0); PG8_MMA(1, 1, At, B1); PG8_BAR; PG8_SCHED;
	s_add_i32 s54, 0, 0x18000
	s_add_i32 s55, 0, 0x1c000
	v_add_u32_e32 v162, s54, v150
	v_add_u32_e32 v178, s55, v150
	ds_read_b128 v[144:147], v162
	ds_read_b128 v[154:157], v162 offset:1024
	ds_read_b128 v[158:161], v162 offset:2048
	ds_read_b128 v[162:165], v162 offset:3072
	ds_read_b128 v[166:169], v178
	ds_read_b128 v[170:173], v178 offset:1024
	ds_read_b128 v[174:177], v178 offset:2048
	ds_read_b128 v[178:181], v178 offset:3072
	s_add_u32 s34, s34, 0x200000
	s_addc_u32 s35, s35, 0
	s_mov_b32 m0, s37
	ds_read_b128 v[182:185], v153 offset:32768
	ds_read_b128 v[188:191], v153 offset:33792
	ds_read_b128 v[192:195], v153 offset:34816
	ds_read_b128 v[196:199], v153 offset:35840
	ds_read_b128 v[200:203], v153 offset:36864
	ds_read_b128 v[204:207], v153 offset:37888
	ds_read_b128 v[208:211], v153 offset:38912
	ds_read_b128 v[212:215], v153 offset:39936
	global_load_lds_dwordx4 v128, s[34:35]
	s_mov_b32 m0, s38
	s_nop 0
	global_load_lds_dwordx4 v132, s[34:35]
	s_waitcnt vmcnt(8)
	s_waitcnt lgkmcnt(0)
	s_barrier
	s_setprio 1
	s_waitcnt lgkmcnt(0)
	v_mfma_f32_16x16x32_bf16 v[124:127], v[144:147], v[182:185], v[124:127]
	v_mfma_f32_16x16x32_bf16 v[120:123], v[158:161], v[182:185], v[120:123]
	v_mfma_f32_16x16x32_bf16 v[112:115], v[144:147], v[192:195], v[112:115]
	v_mfma_f32_16x16x32_bf16 v[104:107], v[158:161], v[192:195], v[104:107]
	v_mfma_f32_16x16x32_bf16 v[96:99], v[144:147], v[200:203], v[96:99]
	v_mfma_f32_16x16x32_bf16 v[88:91], v[158:161], v[200:203], v[88:91]
	v_mfma_f32_16x16x32_bf16 v[80:83], v[144:147], v[208:211], v[80:83]
	v_mfma_f32_16x16x32_bf16 v[72:75], v[158:161], v[208:211], v[72:75]
	v_mfma_f32_16x16x32_bf16 v[124:127], v[154:157], v[188:191], v[124:127]
	v_mfma_f32_16x16x32_bf16 v[120:123], v[162:165], v[188:191], v[120:123]
	v_mfma_f32_16x16x32_bf16 v[112:115], v[154:157], v[196:199], v[112:115]
	v_mfma_f32_16x16x32_bf16 v[104:107], v[162:165], v[196:199], v[104:107]
	v_mfma_f32_16x16x32_bf16 v[96:99], v[154:157], v[204:207], v[96:99]
	v_mfma_f32_16x16x32_bf16 v[88:91], v[162:165], v[204:207], v[88:91]
	v_mfma_f32_16x16x32_bf16 v[80:83], v[154:157], v[212:215], v[80:83]
	v_mfma_f32_16x16x32_bf16 v[72:75], v[162:165], v[212:215], v[72:75]
	v_mfma_f32_16x16x32_bf16 v[116:119], v[166:169], v[182:185], v[116:119]
	v_mfma_f32_16x16x32_bf16 v[108:111], v[174:177], v[182:185], v[108:111]
	v_mfma_f32_16x16x32_bf16 v[100:103], v[166:169], v[192:195], v[100:103]
	v_mfma_f32_16x16x32_bf16 v[92:95], v[174:177], v[192:195], v[92:95]
	v_mfma_f32_16x16x32_bf16 v[84:87], v[166:169], v[200:203], v[84:87]
	v_mfma_f32_16x16x32_bf16 v[76:79], v[174:177], v[200:203], v[76:79]
	v_mfma_f32_16x16x32_bf16 v[68:71], v[166:169], v[208:211], v[68:71]
	v_mfma_f32_16x16x32_bf16 v[64:67], v[174:177], v[208:211], v[64:67]
	v_mfma_f32_16x16x32_bf16 v[116:119], v[170:173], v[188:191], v[116:119]
	v_mfma_f32_16x16x32_bf16 v[108:111], v[178:181], v[188:191], v[108:111]
	v_mfma_f32_16x16x32_bf16 v[100:103], v[170:173], v[196:199], v[100:103]
	v_mfma_f32_16x16x32_bf16 v[92:95], v[178:181], v[196:199], v[92:95]
	v_mfma_f32_16x16x32_bf16 v[84:87], v[170:173], v[204:207], v[84:87]
	v_mfma_f32_16x16x32_bf16 v[76:79], v[178:181], v[204:207], v[76:79]
	v_mfma_f32_16x16x32_bf16 v[68:71], v[170:173], v[212:215], v[68:71]
	v_mfma_f32_16x16x32_bf16 v[64:67], v[178:181], v[212:215], v[64:67]
	s_setprio 0
	s_barrier
	s_add_i32 s34, s54, s1
	s_mov_b32 m0, s34
	s_nop 0
	global_load_lds_dwordx4 v130, s[98:99]
	s_add_i32 m0, s34, 0x2000
	s_add_u32 s30, s30, 0x200080
	s_addc_u32 s31, s31, 0
	s_add_i32 s34, s55, s1
	global_load_lds_dwordx4 v134, s[98:99]
	s_mov_b32 m0, s34
	s_nop 0
	global_load_lds_dwordx4 v130, s[30:31]
	s_add_i32 m0, s34, 0x2000
	s_nop 0
	global_load_lds_dwordx4 v134, s[30:31]
	s_mov_b32 m0, s40
	s_nop 0
	global_load_lds_dwordx4 v128, s[100:101]
	s_mov_b32 m0, s41
	s_nop 0
	global_load_lds_dwordx4 v132, s[100:101]
	ds_read_b128 v[182:185], v153 offset:49152
	ds_read_b128 v[188:191], v153 offset:50176
	ds_read_b128 v[192:195], v153 offset:51200
	ds_read_b128 v[196:199], v153 offset:52224
	ds_read_b128 v[200:203], v153 offset:53248
	ds_read_b128 v[204:207], v153 offset:54272
	ds_read_b128 v[208:211], v153 offset:55296
	ds_read_b128 v[212:215], v153 offset:56320
	s_waitcnt vmcnt(8)
	s_waitcnt lgkmcnt(0)
	s_barrier
	s_setprio 1
	s_waitcnt lgkmcnt(0)
	v_mfma_f32_16x16x32_bf16 v[60:63], v[144:147], v[182:185], v[60:63]
	v_mfma_f32_16x16x32_bf16 v[56:59], v[158:161], v[182:185], v[56:59]
	v_mfma_f32_16x16x32_bf16 v[48:51], v[144:147], v[192:195], v[48:51]
	v_mfma_f32_16x16x32_bf16 v[40:43], v[158:161], v[192:195], v[40:43]
	v_mfma_f32_16x16x32_bf16 v[32:35], v[144:147], v[200:203], v[32:35]
	v_mfma_f32_16x16x32_bf16 v[24:27], v[158:161], v[200:203], v[24:27]
	v_mfma_f32_16x16x32_bf16 v[16:19], v[144:147], v[208:211], v[16:19]
	v_mfma_f32_16x16x32_bf16 v[8:11], v[158:161], v[208:211], v[8:11]
	v_mfma_f32_16x16x32_bf16 v[60:63], v[154:157], v[188:191], v[60:63]
	v_mfma_f32_16x16x32_bf16 v[56:59], v[162:165], v[188:191], v[56:59]
	v_mfma_f32_16x16x32_bf16 v[48:51], v[154:157], v[196:199], v[48:51]
	v_mfma_f32_16x16x32_bf16 v[40:43], v[162:165], v[196:199], v[40:43]
	v_mfma_f32_16x16x32_bf16 v[32:35], v[154:157], v[204:207], v[32:35]
	v_mfma_f32_16x16x32_bf16 v[24:27], v[162:165], v[204:207], v[24:27]
	v_mfma_f32_16x16x32_bf16 v[16:19], v[154:157], v[212:215], v[16:19]
	v_mfma_f32_16x16x32_bf16 v[8:11], v[162:165], v[212:215], v[8:11]
	v_mfma_f32_16x16x32_bf16 v[52:55], v[166:169], v[182:185], v[52:55]
	v_mfma_f32_16x16x32_bf16 v[44:47], v[174:177], v[182:185], v[44:47]
	v_mfma_f32_16x16x32_bf16 v[36:39], v[166:169], v[192:195], v[36:39]
	v_mfma_f32_16x16x32_bf16 v[28:31], v[174:177], v[192:195], v[28:31]
	v_mfma_f32_16x16x32_bf16 v[20:23], v[166:169], v[200:203], v[20:23]
	v_mfma_f32_16x16x32_bf16 v[12:15], v[174:177], v[200:203], v[12:15]
	v_mfma_f32_16x16x32_bf16 v[4:7], v[166:169], v[208:211], v[4:7]
	v_mfma_f32_16x16x32_bf16 v[0:3], v[174:177], v[208:211], v[0:3]
	v_mfma_f32_16x16x32_bf16 v[52:55], v[170:173], v[188:191], v[52:55]
	v_mfma_f32_16x16x32_bf16 v[44:47], v[178:181], v[188:191], v[44:47]
	v_mfma_f32_16x16x32_bf16 v[36:39], v[170:173], v[196:199], v[36:39]
	v_mfma_f32_16x16x32_bf16 v[28:31], v[178:181], v[196:199], v[28:31]
	v_mfma_f32_16x16x32_bf16 v[20:23], v[170:173], v[204:207], v[20:23]
	v_mfma_f32_16x16x32_bf16 v[12:15], v[178:181], v[204:207], v[12:15]
	v_mfma_f32_16x16x32_bf16 v[4:7], v[170:173], v[212:215], v[4:7]
	v_mfma_f32_16x16x32_bf16 v[0:3], v[178:181], v[212:215], v[0:3]
	s_setprio 0
	s_barrier
	s_add_i32 s51, s51, 2
	s_add_u32 s28, s28, 0x100
	s_addc_u32 s29, s29, 0
	s_add_u32 s49, s49, 0x100
	s_addc_u32 s50, s50, 0
	s_cmpk_gt_u32 s51, 0x7d
	s_cbranch_scc0 .LBB0_803
	s_and_b64 vcc, exec, s[16:17]
	s_cbranch_vccz .LBB0_806
	s_barrier

; #define PG8_STAGE(bufoff, gbase, voff) do { _Pragma("unroll") for (int _i = 0; _i < 2; ++_i) \
;         __builtin_amdgcn_global_load_lds((const unsigned*)((const char*)(gbase) + (voff)[_i]), (PG8_LAS unsigned*)(lds + (bufoff) + ldsw + _i * 8192), 16, 0, 0); } while (0)
; #define PG8_LDA(dst, b, h) do { _Pragma("unroll") for (int m = 0; m < 4; ++m) _Pragma("unroll") for (int k = 0; k < 2; ++k) dst[m][k] = *(const PG8_LAS bf16x8*)(lds + PG8_SA(b, h) + aoff + m * 2048 + k * 1024); } while (0)
; #define PG8_LDB(dst, b, h) do { _Pragma("unroll") for (int n = 0; n < 2; ++n) _Pragma("unroll") for (int k = 0; k < 2; ++k) dst[n][k] = *(const PG8_LAS bf16x8*)(lds + PG8_SB(b, h) + boff + n * 2048 + k * 1024); } while (0)
; #define PG8_MMA(ai, bj, At, Bt) do { __builtin_amdgcn_s_setprio(1); _Pragma("unroll") for (int m = 0; m < 4; ++m) _Pragma("unroll") for (int n = 0; n < 2; ++n) _Pragma("unroll") for (int k = 0; k < 2; ++k) \
;         acc[ai][bj][m][n] = __builtin_amdgcn_mfma_f32_16x16x32_bf16(Bt[n][k], At[m][k], acc[ai][bj][m][n], 0, 0, 0); __builtin_amdgcn_s_setprio(0); } while (0)
; #define PG8_WAIT_V(n) asm volatile("s_waitcnt vmcnt(" #n ")" ::: "memory")
; #define PG8_WAIT_L(n) asm volatile("s_waitcnt lgkmcnt(" #n ")" ::: "memory")
; template <class Epi, class Sched, bool ALIGN_EPI = false, bool SP2 = false>
; __device__ __forceinline__ void gemm_phase(PG8_LAS unsigned char* lds, const Gemm g, const Sched& S, const Epi& E) {
;     ...
;             const bool last = (t == nt - 2);
;             const char* a1 = cA + (size_t)(t + 1) * kstep;
;             const char* a2 = last ? nA : cA + (size_t)(t + 2) * kstep; const char* b2 = last ? nB : cB + (size_t)(t + 2) * kstep;
;             const char* a3 = a2 + kstep; const char* b3 = b2 + kstep;
;             if (last && has_next) S.a_ready(nxt);
;             if constexpr (SP2) {
;             PG8_LDB(B0, 0, 0); PG8_LDB(B1, 0, 1); PG8_SCHED; PG8_LDA(At, 0, 0); PG8_STAGE(PG8_SA(1, 1), a1 + hstep, voffA);
;             PG8_WAIT_V(8); PG8_WAIT_L(0); PG8_BAR; PG8_MMA(0, 0, At, B0); PG8_MMA(0, 1, At, B1); PG8_BAR; PG8_SCHED;
;             PG8_LDA(At, 0, 1); PG8_STAGE(PG8_SB(0, 0), b2, voffB); PG8_STAGE(PG8_SB(0, 1), b2 + hstep, voffB); PG8_STAGE(PG8_SA(0, 0), a2, voffA);
;             PG8_WAIT_V(8); PG8_WAIT_L(0); PG8_BAR; PG8_MMA(1, 0, At, B0); PG8_MMA(1, 1, At, B1); PG8_BAR; PG8_SCHED;
.LBB0_921:
	ds_read_b128 v[144:147], v151
	ds_read_b128 v[156:159], v151 offset:1024
	ds_read_b128 v[160:163], v151 offset:2048
	ds_read_b128 v[164:167], v151 offset:3072
	ds_read_b128 v[168:171], v152
	ds_read_b128 v[172:175], v152 offset:1024
	ds_read_b128 v[176:179], v152 offset:2048
	ds_read_b128 v[180:183], v152 offset:3072
	s_add_u32 s30, s28, 0xfff80080
	s_addc_u32 s31, s29, -1
	s_cmp_eq_u32 s53, 28
	s_cselect_b32 s35, s21, s31
	s_cselect_b32 s34, s49, s30
	s_cselect_b32 s31, s19, s52
	s_cselect_b32 s30, s50, s51
	s_add_i32 m0, s27, 0xc000
	ds_read_b128 v[188:191], v153
	ds_read_b128 v[192:195], v153 offset:1024
	ds_read_b128 v[196:199], v153 offset:2048
	ds_read_b128 v[200:203], v153 offset:3072
	ds_read_b128 v[204:207], v153 offset:4096
	ds_read_b128 v[208:211], v153 offset:5120
	ds_read_b128 v[212:215], v153 offset:6144
	ds_read_b128 v[216:219], v153 offset:7168
	global_load_lds_dwordx4 v136, s[28:29]
	s_add_i32 m0, s27, 0xe000
	s_nop 0
	global_load_lds_dwordx4 v138, s[28:29]
	s_waitcnt vmcnt(8)
	s_waitcnt lgkmcnt(0)
	s_barrier
	s_setprio 1
	s_waitcnt lgkmcnt(0)
	v_mfma_f32_16x16x32_bf16 v[124:127], v[144:147], v[188:191], v[124:127]
	v_mfma_f32_16x16x32_bf16 v[120:123], v[160:163], v[188:191], v[120:123]
	v_mfma_f32_16x16x32_bf16 v[108:111], v[144:147], v[196:199], v[108:111]
	v_mfma_f32_16x16x32_bf16 v[104:107], v[160:163], v[196:199], v[104:107]
	v_mfma_f32_16x16x32_bf16 v[92:95], v[144:147], v[204:207], v[92:95]
	v_mfma_f32_16x16x32_bf16 v[88:91], v[160:163], v[204:207], v[88:91]
	v_mfma_f32_16x16x32_bf16 v[76:79], v[144:147], v[212:215], v[76:79]
	v_mfma_f32_16x16x32_bf16 v[72:75], v[160:163], v[212:215], v[72:75]
	v_mfma_f32_16x16x32_bf16 v[124:127], v[156:159], v[192:195], v[124:127]
	v_mfma_f32_16x16x32_bf16 v[120:123], v[164:167], v[192:195], v[120:123]
	v_mfma_f32_16x16x32_bf16 v[108:111], v[156:159], v[200:203], v[108:111]
	v_mfma_f32_16x16x32_bf16 v[104:107], v[164:167], v[200:203], v[104:107]
	v_mfma_f32_16x16x32_bf16 v[92:95], v[156:159], v[208:211], v[92:95]
	v_mfma_f32_16x16x32_bf16 v[88:91], v[164:167], v[208:211], v[88:91]
	v_mfma_f32_16x16x32_bf16 v[76:79], v[156:159], v[216:219], v[76:79]
	v_mfma_f32_16x16x32_bf16 v[72:75], v[164:167], v[216:219], v[72:75]
	v_mfma_f32_16x16x32_bf16 v[116:119], v[168:171], v[188:191], v[116:119]
	v_mfma_f32_16x16x32_bf16 v[112:115], v[176:179], v[188:191], v[112:115]
	v_mfma_f32_16x16x32_bf16 v[100:103], v[168:171], v[196:199], v[100:103]
	v_mfma_f32_16x16x32_bf16 v[96:99], v[176:179], v[196:199], v[96:99]
	v_mfma_f32_16x16x32_bf16 v[84:87], v[168:171], v[204:207], v[84:87]
	v_mfma_f32_16x16x32_bf16 v[80:83], v[176:179], v[204:207], v[80:83]
	v_mfma_f32_16x16x32_bf16 v[68:71], v[168:171], v[212:215], v[68:71]
	v_mfma_f32_16x16x32_bf16 v[64:67], v[176:179], v[212:215], v[64:67]
	v_mfma_f32_16x16x32_bf16 v[116:119], v[172:175], v[192:195], v[116:119]
	v_mfma_f32_16x16x32_bf16 v[112:115], v[180:183], v[192:195], v[112:115]
	v_mfma_f32_16x16x32_bf16 v[100:103], v[172:175], v[200:203], v[100:103]
	v_mfma_f32_16x16x32_bf16 v[96:99], v[180:183], v[200:203], v[96:99]
	v_mfma_f32_16x16x32_bf16 v[84:87], v[172:175], v[208:211], v[84:87]
	v_mfma_f32_16x16x32_bf16 v[80:83], v[180:183], v[208:211], v[80:83]
	v_mfma_f32_16x16x32_bf16 v[68:71], v[172:175], v[216:219], v[68:71]
	v_mfma_f32_16x16x32_bf16 v[64:67], v[180:183], v[216:219], v[64:67]
	s_setprio 0
	s_barrier
	s_add_u32 s98, s30, s14
	s_addc_u32 s99, s31, s15
	s_add_u32 s100, s34, s14
	s_addc_u32 s101, s35, s15
	s_add_i32 s54, s45, s1
	s_mov_b32 m0, s54
	s_nop 0
	global_load_lds_dwordx4 v130, s[30:31]
	s_add_i32 m0, s54, 0x2000
	s_add_u32 s54, s30, 0x80000
	s_addc_u32 s55, s31, 0
	s_add_i32 s56, s46, s1
	global_load_lds_dwordx4 v134, s[30:31]
	s_mov_b32 m0, s56
	s_nop 0
	global_load_lds_dwordx4 v130, s[54:55]
	s_add_i32 m0, s56, 0x2000
	s_nop 0
	global_load_lds_dwordx4 v134, s[54:55]
	s_mov_b32 m0, s27
	s_nop 0
	global_load_lds_dwordx4 v128, s[34:35]
	s_mov_b32 m0, s36
	s_nop 0
	global_load_lds_dwordx4 v132, s[34:35]
	ds_read_b128 v[188:191], v153 offset:16384
	ds_read_b128 v[192:195], v153 offset:17408
	ds_read_b128 v[196:199], v153 offset:18432
	ds_read_b128 v[200:203], v153 offset:19456
	ds_read_b128 v[204:207], v153 offset:20480
	ds_read_b128 v[208:211], v153 offset:21504
	ds_read_b128 v[212:215], v153 offset:22528
	ds_read_b128 v[216:219], v153 offset:23552
	s_waitcnt vmcnt(8)
	s_waitcnt lgkmcnt(0)
	s_barrier
	s_setprio 1
	s_waitcnt lgkmcnt(0)
	v_mfma_f32_16x16x32_bf16 v[60:63], v[144:147], v[188:191], v[60:63]
	v_mfma_f32_16x16x32_bf16 v[56:59], v[160:163], v[188:191], v[56:59]
	v_mfma_f32_16x16x32_bf16 v[44:47], v[144:147], v[196:199], v[44:47]
	v_mfma_f32_16x16x32_bf16 v[40:43], v[160:163], v[196:199], v[40:43]
	v_mfma_f32_16x16x32_bf16 v[28:31], v[144:147], v[204:207], v[28:31]
	v_mfma_f32_16x16x32_bf16 v[24:27], v[160:163], v[204:207], v[24:27]
	v_mfma_f32_16x16x32_bf16 v[12:15], v[144:147], v[212:215], v[12:15]
	v_mfma_f32_16x16x32_bf16 v[8:11], v[160:163], v[212:215], v[8:11]
	v_mfma_f32_16x16x32_bf16 v[60:63], v[156:159], v[192:195], v[60:63]
	v_mfma_f32_16x16x32_bf16 v[56:59], v[164:167], v[192:195], v[56:59]
	v_mfma_f32_16x16x32_bf16 v[44:47], v[156:159], v[200:203], v[44:47]
	v_mfma_f32_16x16x32_bf16 v[40:43], v[164:167], v[200:203], v[40:43]
	v_mfma_f32_16x16x32_bf16 v[28:31], v[156:159], v[208:211], v[28:31]
	v_mfma_f32_16x16x32_bf16 v[24:27], v[164:167], v[208:211], v[24:27]
	v_mfma_f32_16x16x32_bf16 v[12:15], v[156:159], v[216:219], v[12:15]
	v_mfma_f32_16x16x32_bf16 v[8:11], v[164:167], v[216:219], v[8:11]
	v_mfma_f32_16x16x32_bf16 v[52:55], v[168:171], v[188:191], v[52:55]
	v_mfma_f32_16x16x32_bf16 v[48:51], v[176:179], v[188:191], v[48:51]
	v_mfma_f32_16x16x32_bf16 v[36:39], v[168:171], v[196:199], v[36:39]
	v_mfma_f32_16x16x32_bf16 v[32:35], v[176:179], v[196:199], v[32:35]
	v_mfma_f32_16x16x32_bf16 v[20:23], v[168:171], v[204:207], v[20:23]
	v_mfma_f32_16x16x32_bf16 v[16:19], v[176:179], v[204:207], v[16:19]
	v_mfma_f32_16x16x32_bf16 v[4:7], v[168:171], v[212:215], v[4:7]
	v_mfma_f32_16x16x32_bf16 v[0:3], v[176:179], v[212:215], v[0:3]
	v_mfma_f32_16x16x32_bf16 v[52:55], v[172:175], v[192:195], v[52:55]
	v_mfma_f32_16x16x32_bf16 v[48:51], v[180:183], v[192:195], v[48:51]
	v_mfma_f32_16x16x32_bf16 v[36:39], v[172:175], v[200:203], v[36:39]
	v_mfma_f32_16x16x32_bf16 v[32:35], v[180:183], v[200:203], v[32:35]
	v_mfma_f32_16x16x32_bf16 v[20:23], v[172:175], v[208:211], v[20:23]
	v_mfma_f32_16x16x32_bf16 v[16:19], v[180:183], v[208:211], v[16:19]
	v_mfma_f32_16x16x32_bf16 v[4:7], v[172:175], v[216:219], v[4:7]
	v_mfma_f32_16x16x32_bf16 v[0:3], v[180:183], v[216:219], v[0:3]
	s_setprio 0
	s_barrier
; #define PG8_STAGE(bufoff, gbase, voff) do { _Pragma("unroll") for (int _i = 0; _i < 2; ++_i) \
;         __builtin_amdgcn_global_load_lds((const unsigned*)((const char*)(gbase) + (voff)[_i]), (PG8_LAS unsigned*)(lds + (bufoff) + ldsw + _i * 8192), 16, 0, 0); } while (0)
; #define PG8_LDA(dst, b, h) do { _Pragma("unroll") for (int m = 0; m < 4; ++m) _Pragma("unroll") for (int k = 0; k < 2; ++k) dst[m][k] = *(const PG8_LAS bf16x8*)(lds + PG8_SA(b, h) + aoff + m * 2048 + k * 1024); } while (0)
; #define PG8_LDB(dst, b, h) do { _Pragma("unroll") for (int n = 0; n < 2; ++n) _Pragma("unroll") for (int k = 0; k < 2; ++k) dst[n][k] = *(const PG8_LAS bf16x8*)(lds + PG8_SB(b, h) + boff + n * 2048 + k * 1024); } while (0)
; #define PG8_MMA(ai, bj, At, Bt) do { __builtin_amdgcn_s_setprio(1); _Pragma("unroll") for (int m = 0; m < 4; ++m) _Pragma("unroll") for (int n = 0; n < 2; ++n) _Pragma("unroll") for (int k = 0; k < 2; ++k) \
;         acc[ai][bj][m][n] = __builtin_amdgcn_mfma_f32_16x16x32_bf16(Bt[n][k], At[m][k], acc[ai][bj][m][n], 0, 0, 0); __builtin_amdgcn_s_setprio(0); } while (0)
; #define PG8_WAIT_V(n) asm volatile("s_waitcnt vmcnt(" #n ")" ::: "memory")
; #define PG8_WAIT_L(n) asm volatile("s_waitcnt lgkmcnt(" #n ")" ::: "memory")
; #define PG8_BAR __builtin_amdgcn_s_barrier()
; #define PG8_SCHED __builtin_amdgcn_sched_barrier(0)
; template <class Epi, class Sched, bool ALIGN_EPI = false, bool SP2 = false>
; __device__ __forceinline__ void gemm_phase(PG8_LAS unsigned char* lds, const Gemm g, const Sched& S, const Epi& E) {
;     ...
;             PG8_LDB(B0, 1, 0); PG8_LDB(B1, 1, 1); PG8_SCHED; PG8_LDA(At, 1, 0); PG8_STAGE(PG8_SA(0, 1), a2 + hstep, voffA);
;             PG8_WAIT_V(8); PG8_WAIT_L(0); PG8_BAR; PG8_MMA(0, 0, At, B0); PG8_MMA(0, 1, At, B1); PG8_BAR; PG8_SCHED;
;             PG8_LDA(At, 1, 1); PG8_STAGE(PG8_SB(1, 0), b3, voffB); PG8_STAGE(PG8_SB(1, 1), b3 + hstep, voffB); PG8_STAGE(PG8_SA(1, 0), a3, voffA);
;             PG8_WAIT_V(8); PG8_WAIT_L(0); PG8_BAR; PG8_MMA(1, 0, At, B0); PG8_MMA(1, 1, At, B1); PG8_BAR; PG8_SCHED;
	s_add_i32 s54, 0, 0x18000
	v_add_u32_e32 v155, s54, v150
	s_add_i32 s55, 0, 0x1c000
	ds_read_b128 v[144:147], v155
	ds_read_b128 v[156:159], v155 offset:1024
	ds_read_b128 v[160:163], v155 offset:2048
	ds_read_b128 v[164:167], v155 offset:3072
	v_add_u32_e32 v155, s55, v150
	ds_read_b128 v[168:171], v155
	ds_read_b128 v[172:175], v155 offset:1024
	ds_read_b128 v[176:179], v155 offset:2048
	ds_read_b128 v[180:183], v155 offset:3072
	s_add_u32 s34, s34, 0x80000
	s_addc_u32 s35, s35, 0
	s_mov_b32 m0, s37
	ds_read_b128 v[188:191], v153 offset:32768
	ds_read_b128 v[192:195], v153 offset:33792
	ds_read_b128 v[196:199], v153 offset:34816
	ds_read_b128 v[200:203], v153 offset:35840
	ds_read_b128 v[204:207], v153 offset:36864
	ds_read_b128 v[208:211], v153 offset:37888
	ds_read_b128 v[212:215], v153 offset:38912
	ds_read_b128 v[216:219], v153 offset:39936
	global_load_lds_dwordx4 v128, s[34:35]
	s_mov_b32 m0, s38
	s_nop 0
	global_load_lds_dwordx4 v132, s[34:35]
	s_waitcnt vmcnt(8)
	s_waitcnt lgkmcnt(0)
	s_barrier
	s_setprio 1
	s_waitcnt lgkmcnt(0)
	v_mfma_f32_16x16x32_bf16 v[124:127], v[144:147], v[188:191], v[124:127]
	v_mfma_f32_16x16x32_bf16 v[120:123], v[160:163], v[188:191], v[120:123]
	v_mfma_f32_16x16x32_bf16 v[108:111], v[144:147], v[196:199], v[108:111]
	v_mfma_f32_16x16x32_bf16 v[104:107], v[160:163], v[196:199], v[104:107]
	v_mfma_f32_16x16x32_bf16 v[92:95], v[144:147], v[204:207], v[92:95]
	v_mfma_f32_16x16x32_bf16 v[88:91], v[160:163], v[204:207], v[88:91]
	v_mfma_f32_16x16x32_bf16 v[76:79], v[144:147], v[212:215], v[76:79]
	v_mfma_f32_16x16x32_bf16 v[72:75], v[160:163], v[212:215], v[72:75]
	v_mfma_f32_16x16x32_bf16 v[124:127], v[156:159], v[192:195], v[124:127]
	v_mfma_f32_16x16x32_bf16 v[120:123], v[164:167], v[192:195], v[120:123]
	v_mfma_f32_16x16x32_bf16 v[108:111], v[156:159], v[200:203], v[108:111]
	v_mfma_f32_16x16x32_bf16 v[104:107], v[164:167], v[200:203], v[104:107]
	v_mfma_f32_16x16x32_bf16 v[92:95], v[156:159], v[208:211], v[92:95]
	v_mfma_f32_16x16x32_bf16 v[88:91], v[164:167], v[208:211], v[88:91]
	v_mfma_f32_16x16x32_bf16 v[76:79], v[156:159], v[216:219], v[76:79]
	v_mfma_f32_16x16x32_bf16 v[72:75], v[164:167], v[216:219], v[72:75]
	v_mfma_f32_16x16x32_bf16 v[116:119], v[168:171], v[188:191], v[116:119]
	v_mfma_f32_16x16x32_bf16 v[112:115], v[176:179], v[188:191], v[112:115]
	v_mfma_f32_16x16x32_bf16 v[100:103], v[168:171], v[196:199], v[100:103]
	v_mfma_f32_16x16x32_bf16 v[96:99], v[176:179], v[196:199], v[96:99]
	v_mfma_f32_16x16x32_bf16 v[84:87], v[168:171], v[204:207], v[84:87]
	v_mfma_f32_16x16x32_bf16 v[80:83], v[176:179], v[204:207], v[80:83]
	v_mfma_f32_16x16x32_bf16 v[68:71], v[168:171], v[212:215], v[68:71]
	v_mfma_f32_16x16x32_bf16 v[64:67], v[176:179], v[212:215], v[64:67]
	v_mfma_f32_16x16x32_bf16 v[116:119], v[172:175], v[192:195], v[116:119]
	v_mfma_f32_16x16x32_bf16 v[112:115], v[180:183], v[192:195], v[112:115]
	v_mfma_f32_16x16x32_bf16 v[100:103], v[172:175], v[200:203], v[100:103]
	v_mfma_f32_16x16x32_bf16 v[96:99], v[180:183], v[200:203], v[96:99]
	v_mfma_f32_16x16x32_bf16 v[84:87], v[172:175], v[208:211], v[84:87]
	v_mfma_f32_16x16x32_bf16 v[80:83], v[180:183], v[208:211], v[80:83]
	v_mfma_f32_16x16x32_bf16 v[68:71], v[172:175], v[216:219], v[68:71]
	v_mfma_f32_16x16x32_bf16 v[64:67], v[180:183], v[216:219], v[64:67]
	s_setprio 0
	s_barrier
	s_add_i32 s34, s54, s1
	s_mov_b32 m0, s34
	s_nop 0
	global_load_lds_dwordx4 v130, s[98:99]
	s_add_i32 m0, s34, 0x2000
	s_add_u32 s30, s30, 0x80080
	s_addc_u32 s31, s31, 0
	s_add_i32 s34, s55, s1
	global_load_lds_dwordx4 v134, s[98:99]
	s_mov_b32 m0, s34
	s_nop 0
	global_load_lds_dwordx4 v130, s[30:31]
	s_add_i32 m0, s34, 0x2000
	s_nop 0
	global_load_lds_dwordx4 v134, s[30:31]
	s_mov_b32 m0, s42
	s_nop 0
	global_load_lds_dwordx4 v128, s[100:101]
	s_mov_b32 m0, s43
	s_nop 0
	global_load_lds_dwordx4 v132, s[100:101]
	ds_read_b128 v[188:191], v153 offset:49152
	ds_read_b128 v[192:195], v153 offset:50176
	ds_read_b128 v[196:199], v153 offset:51200
	ds_read_b128 v[200:203], v153 offset:52224
	ds_read_b128 v[204:207], v153 offset:53248
	ds_read_b128 v[208:211], v153 offset:54272
	ds_read_b128 v[212:215], v153 offset:55296
	ds_read_b128 v[216:219], v153 offset:56320
	s_waitcnt vmcnt(8)
	s_waitcnt lgkmcnt(0)
	s_barrier
	s_setprio 1
	s_waitcnt lgkmcnt(0)
	v_mfma_f32_16x16x32_bf16 v[60:63], v[144:147], v[188:191], v[60:63]
	v_mfma_f32_16x16x32_bf16 v[56:59], v[160:163], v[188:191], v[56:59]
	v_mfma_f32_16x16x32_bf16 v[44:47], v[144:147], v[196:199], v[44:47]
	v_mfma_f32_16x16x32_bf16 v[40:43], v[160:163], v[196:199], v[40:43]
	v_mfma_f32_16x16x32_bf16 v[28:31], v[144:147], v[204:207], v[28:31]
	v_mfma_f32_16x16x32_bf16 v[24:27], v[160:163], v[204:207], v[24:27]
	v_mfma_f32_16x16x32_bf16 v[12:15], v[144:147], v[212:215], v[12:15]
	v_mfma_f32_16x16x32_bf16 v[8:11], v[160:163], v[212:215], v[8:11]
	v_mfma_f32_16x16x32_bf16 v[60:63], v[156:159], v[192:195], v[60:63]
	v_mfma_f32_16x16x32_bf16 v[56:59], v[164:167], v[192:195], v[56:59]
	v_mfma_f32_16x16x32_bf16 v[44:47], v[156:159], v[200:203], v[44:47]
	v_mfma_f32_16x16x32_bf16 v[40:43], v[164:167], v[200:203], v[40:43]
	v_mfma_f32_16x16x32_bf16 v[28:31], v[156:159], v[208:211], v[28:31]
	v_mfma_f32_16x16x32_bf16 v[24:27], v[164:167], v[208:211], v[24:27]
	v_mfma_f32_16x16x32_bf16 v[12:15], v[156:159], v[216:219], v[12:15]
	v_mfma_f32_16x16x32_bf16 v[8:11], v[164:167], v[216:219], v[8:11]
	v_mfma_f32_16x16x32_bf16 v[52:55], v[168:171], v[188:191], v[52:55]
	v_mfma_f32_16x16x32_bf16 v[48:51], v[176:179], v[188:191], v[48:51]
	v_mfma_f32_16x16x32_bf16 v[36:39], v[168:171], v[196:199], v[36:39]
	v_mfma_f32_16x16x32_bf16 v[32:35], v[176:179], v[196:199], v[32:35]
	v_mfma_f32_16x16x32_bf16 v[20:23], v[168:171], v[204:207], v[20:23]
	v_mfma_f32_16x16x32_bf16 v[16:19], v[176:179], v[204:207], v[16:19]
	v_mfma_f32_16x16x32_bf16 v[4:7], v[168:171], v[212:215], v[4:7]
	v_mfma_f32_16x16x32_bf16 v[0:3], v[176:179], v[212:215], v[0:3]
	v_mfma_f32_16x16x32_bf16 v[52:55], v[172:175], v[192:195], v[52:55]
	v_mfma_f32_16x16x32_bf16 v[48:51], v[180:183], v[192:195], v[48:51]
	v_mfma_f32_16x16x32_bf16 v[36:39], v[172:175], v[200:203], v[36:39]
	v_mfma_f32_16x16x32_bf16 v[32:35], v[180:183], v[200:203], v[32:35]
	v_mfma_f32_16x16x32_bf16 v[20:23], v[172:175], v[208:211], v[20:23]
	v_mfma_f32_16x16x32_bf16 v[16:19], v[180:183], v[208:211], v[16:19]
	v_mfma_f32_16x16x32_bf16 v[4:7], v[172:175], v[216:219], v[4:7]
	v_mfma_f32_16x16x32_bf16 v[0:3], v[180:183], v[216:219], v[0:3]
	s_setprio 0
	s_barrier
	s_add_i32 s53, s53, 2
	s_add_u32 s28, s28, 0x100
	s_addc_u32 s29, s29, 0
	s_add_u32 s51, s51, 0x100
	s_addc_u32 s52, s52, 0
	s_cmp_gt_u32 s53, 29
	s_cbranch_scc0 .LBB0_921
	s_and_b64 vcc, exec, s[16:17]
	s_cbranch_vccz .LBB0_924
	s_barrier

; #define PG8_STAGE(bufoff, gbase, voff) do { _Pragma("unroll") for (int _i = 0; _i < 2; ++_i) \
;         __builtin_amdgcn_global_load_lds((const unsigned*)((const char*)(gbase) + (voff)[_i]), (PG8_LAS unsigned*)(lds + (bufoff) + ldsw + _i * 8192), 16, 0, 0); } while (0)
; #define PG8_LDA(dst, b, h) do { _Pragma("unroll") for (int m = 0; m < 4; ++m) _Pragma("unroll") for (int k = 0; k < 2; ++k) dst[m][k] = *(const PG8_LAS bf16x8*)(lds + PG8_SA(b, h) + aoff + m * 2048 + k * 1024); } while (0)
; #define PG8_LDB(dst, b, h) do { _Pragma("unroll") for (int n = 0; n < 2; ++n) _Pragma("unroll") for (int k = 0; k < 2; ++k) dst[n][k] = *(const PG8_LAS bf16x8*)(lds + PG8_SB(b, h) + boff + n * 2048 + k * 1024); } while (0)
; #define PG8_MMA(ai, bj, At, Bt) do { __builtin_amdgcn_s_setprio(1); _Pragma("unroll") for (int m = 0; m < 4; ++m) _Pragma("unroll") for (int n = 0; n < 2; ++n) _Pragma("unroll") for (int k = 0; k < 2; ++k) \
;         acc[ai][bj][m][n] = __builtin_amdgcn_mfma_f32_16x16x32_bf16(Bt[n][k], At[m][k], acc[ai][bj][m][n], 0, 0, 0); __builtin_amdgcn_s_setprio(0); } while (0)
; #define PG8_WAIT_V(n) asm volatile("s_waitcnt vmcnt(" #n ")" ::: "memory")
; #define PG8_WAIT_L(n) asm volatile("s_waitcnt lgkmcnt(" #n ")" ::: "memory")
; template <class Epi, class Sched, bool ALIGN_EPI = false, bool SP2 = false>
; __device__ __forceinline__ void gemm_phase(PG8_LAS unsigned char* lds, const Gemm g, const Sched& S, const Epi& E) {
;     ...
;             const bool last = (t == nt - 2);
;             const char* a1 = cA + (size_t)(t + 1) * kstep;
;             const char* a2 = last ? nA : cA + (size_t)(t + 2) * kstep; const char* b2 = last ? nB : cB + (size_t)(t + 2) * kstep;
;             const char* a3 = a2 + kstep; const char* b3 = b2 + kstep;
;             if (last && has_next) S.a_ready(nxt);
;             if constexpr (SP2) {
;             PG8_LDB(B0, 0, 0); PG8_LDB(B1, 0, 1); PG8_SCHED; PG8_LDA(At, 0, 0); PG8_STAGE(PG8_SA(1, 1), a1 + hstep, voffA);
;             PG8_WAIT_V(8); PG8_WAIT_L(0); PG8_BAR; PG8_MMA(0, 0, At, B0); PG8_MMA(0, 1, At, B1); PG8_BAR; PG8_SCHED;
;             PG8_LDA(At, 0, 1); PG8_STAGE(PG8_SB(0, 0), b2, voffB); PG8_STAGE(PG8_SB(0, 1), b2 + hstep, voffB); PG8_STAGE(PG8_SA(0, 0), a2, voffA);
;             PG8_WAIT_V(8); PG8_WAIT_L(0); PG8_BAR; PG8_MMA(1, 0, At, B0); PG8_MMA(1, 1, At, B1); PG8_BAR; PG8_SCHED;
.LBB0_996:
	ds_read_b128 v[144:147], v151
	ds_read_b128 v[154:157], v151 offset:1024
	ds_read_b128 v[158:161], v151 offset:2048
	ds_read_b128 v[162:165], v151 offset:3072
	ds_read_b128 v[166:169], v152
	ds_read_b128 v[170:173], v152 offset:1024
	ds_read_b128 v[174:177], v152 offset:2048
	ds_read_b128 v[178:181], v152 offset:3072
	s_add_u32 s28, s26, 0xffe00080
	s_addc_u32 s29, s27, -1
	s_cmpk_eq_i32 s52, 0x7c
	s_cselect_b32 s31, s19, s29
	s_cselect_b32 s30, s48, s28
	s_cselect_b32 s29, s17, s51
	s_cselect_b32 s28, s49, s50
	s_add_i32 m0, s25, 0xc000
	ds_read_b128 v[182:185], v153
	ds_read_b128 v[186:189], v153 offset:1024
	ds_read_b128 v[190:193], v153 offset:2048
	ds_read_b128 v[194:197], v153 offset:3072
	ds_read_b128 v[198:201], v153 offset:4096
	ds_read_b128 v[202:205], v153 offset:5120
	ds_read_b128 v[206:209], v153 offset:6144
	ds_read_b128 v[210:213], v153 offset:7168
	global_load_lds_dwordx4 v136, s[26:27]
	s_add_i32 m0, s25, 0xe000
	s_nop 0
	global_load_lds_dwordx4 v138, s[26:27]
	s_waitcnt vmcnt(8)
	s_waitcnt lgkmcnt(0)
	s_barrier
	s_setprio 1
	s_waitcnt lgkmcnt(0)
	v_mfma_f32_16x16x32_bf16 v[124:127], v[144:147], v[182:185], v[124:127]
	v_mfma_f32_16x16x32_bf16 v[120:123], v[158:161], v[182:185], v[120:123]
	v_mfma_f32_16x16x32_bf16 v[112:115], v[144:147], v[190:193], v[112:115]
	v_mfma_f32_16x16x32_bf16 v[104:107], v[158:161], v[190:193], v[104:107]
	v_mfma_f32_16x16x32_bf16 v[96:99], v[144:147], v[198:201], v[96:99]
	v_mfma_f32_16x16x32_bf16 v[88:91], v[158:161], v[198:201], v[88:91]
	v_mfma_f32_16x16x32_bf16 v[80:83], v[144:147], v[206:209], v[80:83]
	v_mfma_f32_16x16x32_bf16 v[72:75], v[158:161], v[206:209], v[72:75]
	v_mfma_f32_16x16x32_bf16 v[124:127], v[154:157], v[186:189], v[124:127]
	v_mfma_f32_16x16x32_bf16 v[120:123], v[162:165], v[186:189], v[120:123]
	v_mfma_f32_16x16x32_bf16 v[112:115], v[154:157], v[194:197], v[112:115]
	v_mfma_f32_16x16x32_bf16 v[104:107], v[162:165], v[194:197], v[104:107]
	v_mfma_f32_16x16x32_bf16 v[96:99], v[154:157], v[202:205], v[96:99]
	v_mfma_f32_16x16x32_bf16 v[88:91], v[162:165], v[202:205], v[88:91]
	v_mfma_f32_16x16x32_bf16 v[80:83], v[154:157], v[210:213], v[80:83]
	v_mfma_f32_16x16x32_bf16 v[72:75], v[162:165], v[210:213], v[72:75]
	v_mfma_f32_16x16x32_bf16 v[116:119], v[166:169], v[182:185], v[116:119]
	v_mfma_f32_16x16x32_bf16 v[108:111], v[174:177], v[182:185], v[108:111]
	v_mfma_f32_16x16x32_bf16 v[100:103], v[166:169], v[190:193], v[100:103]
	v_mfma_f32_16x16x32_bf16 v[92:95], v[174:177], v[190:193], v[92:95]
	v_mfma_f32_16x16x32_bf16 v[84:87], v[166:169], v[198:201], v[84:87]
	v_mfma_f32_16x16x32_bf16 v[76:79], v[174:177], v[198:201], v[76:79]
	v_mfma_f32_16x16x32_bf16 v[68:71], v[166:169], v[206:209], v[68:71]
	v_mfma_f32_16x16x32_bf16 v[64:67], v[174:177], v[206:209], v[64:67]
	v_mfma_f32_16x16x32_bf16 v[116:119], v[170:173], v[186:189], v[116:119]
	v_mfma_f32_16x16x32_bf16 v[108:111], v[178:181], v[186:189], v[108:111]
	v_mfma_f32_16x16x32_bf16 v[100:103], v[170:173], v[194:197], v[100:103]
	v_mfma_f32_16x16x32_bf16 v[92:95], v[178:181], v[194:197], v[92:95]
	v_mfma_f32_16x16x32_bf16 v[84:87], v[170:173], v[202:205], v[84:87]
	v_mfma_f32_16x16x32_bf16 v[76:79], v[178:181], v[202:205], v[76:79]
	v_mfma_f32_16x16x32_bf16 v[68:71], v[170:173], v[210:213], v[68:71]
	v_mfma_f32_16x16x32_bf16 v[64:67], v[178:181], v[210:213], v[64:67]
	s_setprio 0
	s_barrier
	s_add_u32 s98, s28, s12
	s_addc_u32 s99, s29, s13
	s_add_u32 s100, s30, s12
	s_addc_u32 s101, s31, s13
	s_add_i32 s53, s44, s36
	s_mov_b32 m0, s53
	s_nop 0
	global_load_lds_dwordx4 v130, s[28:29]
	s_add_i32 m0, s53, 0x2000
	s_add_u32 s54, s28, 0x200000
	s_addc_u32 s55, s29, 0
	s_add_i32 s53, s45, s36
	global_load_lds_dwordx4 v134, s[28:29]
	s_mov_b32 m0, s53
	s_nop 0
	global_load_lds_dwordx4 v130, s[54:55]
	s_add_i32 m0, s53, 0x2000
	s_nop 0
	global_load_lds_dwordx4 v134, s[54:55]
	s_mov_b32 m0, s25
	s_nop 0
	global_load_lds_dwordx4 v128, s[30:31]
	s_mov_b32 m0, s37
	s_nop 0
	global_load_lds_dwordx4 v132, s[30:31]
	ds_read_b128 v[182:185], v153 offset:16384
	ds_read_b128 v[186:189], v153 offset:17408
	ds_read_b128 v[190:193], v153 offset:18432
	ds_read_b128 v[194:197], v153 offset:19456
	ds_read_b128 v[198:201], v153 offset:20480
	ds_read_b128 v[202:205], v153 offset:21504
	ds_read_b128 v[206:209], v153 offset:22528
	ds_read_b128 v[210:213], v153 offset:23552
	s_waitcnt vmcnt(8)
	s_waitcnt lgkmcnt(0)
	s_barrier
	s_setprio 1
	s_waitcnt lgkmcnt(0)
	v_mfma_f32_16x16x32_bf16 v[60:63], v[144:147], v[182:185], v[60:63]
	v_mfma_f32_16x16x32_bf16 v[56:59], v[158:161], v[182:185], v[56:59]
	v_mfma_f32_16x16x32_bf16 v[48:51], v[144:147], v[190:193], v[48:51]
	v_mfma_f32_16x16x32_bf16 v[40:43], v[158:161], v[190:193], v[40:43]
	v_mfma_f32_16x16x32_bf16 v[32:35], v[144:147], v[198:201], v[32:35]
	v_mfma_f32_16x16x32_bf16 v[24:27], v[158:161], v[198:201], v[24:27]
	v_mfma_f32_16x16x32_bf16 v[16:19], v[144:147], v[206:209], v[16:19]
	v_mfma_f32_16x16x32_bf16 v[8:11], v[158:161], v[206:209], v[8:11]
	v_mfma_f32_16x16x32_bf16 v[60:63], v[154:157], v[186:189], v[60:63]
	v_mfma_f32_16x16x32_bf16 v[56:59], v[162:165], v[186:189], v[56:59]
	v_mfma_f32_16x16x32_bf16 v[48:51], v[154:157], v[194:197], v[48:51]
	v_mfma_f32_16x16x32_bf16 v[40:43], v[162:165], v[194:197], v[40:43]
	v_mfma_f32_16x16x32_bf16 v[32:35], v[154:157], v[202:205], v[32:35]
	v_mfma_f32_16x16x32_bf16 v[24:27], v[162:165], v[202:205], v[24:27]
	v_mfma_f32_16x16x32_bf16 v[16:19], v[154:157], v[210:213], v[16:19]
	v_mfma_f32_16x16x32_bf16 v[8:11], v[162:165], v[210:213], v[8:11]
	v_mfma_f32_16x16x32_bf16 v[52:55], v[166:169], v[182:185], v[52:55]
	v_mfma_f32_16x16x32_bf16 v[44:47], v[174:177], v[182:185], v[44:47]
	v_mfma_f32_16x16x32_bf16 v[36:39], v[166:169], v[190:193], v[36:39]
	v_mfma_f32_16x16x32_bf16 v[28:31], v[174:177], v[190:193], v[28:31]
	v_mfma_f32_16x16x32_bf16 v[20:23], v[166:169], v[198:201], v[20:23]
	v_mfma_f32_16x16x32_bf16 v[12:15], v[174:177], v[198:201], v[12:15]
	v_mfma_f32_16x16x32_bf16 v[4:7], v[166:169], v[206:209], v[4:7]
	v_mfma_f32_16x16x32_bf16 v[0:3], v[174:177], v[206:209], v[0:3]
	v_mfma_f32_16x16x32_bf16 v[52:55], v[170:173], v[186:189], v[52:55]
	v_mfma_f32_16x16x32_bf16 v[44:47], v[178:181], v[186:189], v[44:47]
	v_mfma_f32_16x16x32_bf16 v[36:39], v[170:173], v[194:197], v[36:39]
	v_mfma_f32_16x16x32_bf16 v[28:31], v[178:181], v[194:197], v[28:31]
	v_mfma_f32_16x16x32_bf16 v[20:23], v[170:173], v[202:205], v[20:23]
	v_mfma_f32_16x16x32_bf16 v[12:15], v[178:181], v[202:205], v[12:15]
	v_mfma_f32_16x16x32_bf16 v[4:7], v[170:173], v[210:213], v[4:7]
	v_mfma_f32_16x16x32_bf16 v[0:3], v[178:181], v[210:213], v[0:3]
	s_setprio 0
	s_barrier
; #define PG8_STAGE(bufoff, gbase, voff) do { _Pragma("unroll") for (int _i = 0; _i < 2; ++_i) \
;         __builtin_amdgcn_global_load_lds((const unsigned*)((const char*)(gbase) + (voff)[_i]), (PG8_LAS unsigned*)(lds + (bufoff) + ldsw + _i * 8192), 16, 0, 0); } while (0)
; #define PG8_LDA(dst, b, h) do { _Pragma("unroll") for (int m = 0; m < 4; ++m) _Pragma("unroll") for (int k = 0; k < 2; ++k) dst[m][k] = *(const PG8_LAS bf16x8*)(lds + PG8_SA(b, h) + aoff + m * 2048 + k * 1024); } while (0)
; #define PG8_LDB(dst, b, h) do { _Pragma("unroll") for (int n = 0; n < 2; ++n) _Pragma("unroll") for (int k = 0; k < 2; ++k) dst[n][k] = *(const PG8_LAS bf16x8*)(lds + PG8_SB(b, h) + boff + n * 2048 + k * 1024); } while (0)
; #define PG8_MMA(ai, bj, At, Bt) do { __builtin_amdgcn_s_setprio(1); _Pragma("unroll") for (int m = 0; m < 4; ++m) _Pragma("unroll") for (int n = 0; n < 2; ++n) _Pragma("unroll") for (int k = 0; k < 2; ++k) \
;         acc[ai][bj][m][n] = __builtin_amdgcn_mfma_f32_16x16x32_bf16(Bt[n][k], At[m][k], acc[ai][bj][m][n], 0, 0, 0); __builtin_amdgcn_s_setprio(0); } while (0)
; #define PG8_WAIT_V(n) asm volatile("s_waitcnt vmcnt(" #n ")" ::: "memory")
; #define PG8_WAIT_L(n) asm volatile("s_waitcnt lgkmcnt(" #n ")" ::: "memory")
; #define PG8_BAR __builtin_amdgcn_s_barrier()
; #define PG8_SCHED __builtin_amdgcn_sched_barrier(0)
; template <class Epi, class Sched, bool ALIGN_EPI = false, bool SP2 = false>
; __device__ __forceinline__ void gemm_phase(PG8_LAS unsigned char* lds, const Gemm g, const Sched& S, const Epi& E) {
;     ...
;             PG8_LDB(B0, 1, 0); PG8_LDB(B1, 1, 1); PG8_SCHED; PG8_LDA(At, 1, 0); PG8_STAGE(PG8_SA(0, 1), a2 + hstep, voffA);
;             PG8_WAIT_V(8); PG8_WAIT_L(0); PG8_BAR; PG8_MMA(0, 0, At, B0); PG8_MMA(0, 1, At, B1); PG8_BAR; PG8_SCHED;
;             PG8_LDA(At, 1, 1); PG8_STAGE(PG8_SB(1, 0), b3, voffB); PG8_STAGE(PG8_SB(1, 1), b3 + hstep, voffB); PG8_STAGE(PG8_SA(1, 0), a3, voffA);
;             PG8_WAIT_V(8); PG8_WAIT_L(0); PG8_BAR; PG8_MMA(1, 0, At, B0); PG8_MMA(1, 1, At, B1); PG8_BAR; PG8_SCHED;
	s_add_i32 s53, 0, 0x18000
	s_add_i32 s54, 0, 0x1c000
	v_add_u32_e32 v162, s53, v150
	v_add_u32_e32 v178, s54, v150
	ds_read_b128 v[144:147], v162
	ds_read_b128 v[154:157], v162 offset:1024
	ds_read_b128 v[158:161], v162 offset:2048
	ds_read_b128 v[162:165], v162 offset:3072
	ds_read_b128 v[166:169], v178
	ds_read_b128 v[170:173], v178 offset:1024
	ds_read_b128 v[174:177], v178 offset:2048
	ds_read_b128 v[178:181], v178 offset:3072
	s_add_u32 s30, s30, 0x200000
	s_addc_u32 s31, s31, 0
	s_mov_b32 m0, s38
	ds_read_b128 v[182:185], v153 offset:32768
	ds_read_b128 v[186:189], v153 offset:33792
	ds_read_b128 v[190:193], v153 offset:34816
	ds_read_b128 v[194:197], v153 offset:35840
	ds_read_b128 v[198:201], v153 offset:36864
	ds_read_b128 v[202:205], v153 offset:37888
	ds_read_b128 v[206:209], v153 offset:38912
	ds_read_b128 v[210:213], v153 offset:39936
	global_load_lds_dwordx4 v128, s[30:31]
	s_mov_b32 m0, s39
	s_nop 0
	global_load_lds_dwordx4 v132, s[30:31]
	s_waitcnt vmcnt(8)
	s_waitcnt lgkmcnt(0)
	s_barrier
	s_setprio 1
	s_waitcnt lgkmcnt(0)
	v_mfma_f32_16x16x32_bf16 v[124:127], v[144:147], v[182:185], v[124:127]
	v_mfma_f32_16x16x32_bf16 v[120:123], v[158:161], v[182:185], v[120:123]
	v_mfma_f32_16x16x32_bf16 v[112:115], v[144:147], v[190:193], v[112:115]
	v_mfma_f32_16x16x32_bf16 v[104:107], v[158:161], v[190:193], v[104:107]
	v_mfma_f32_16x16x32_bf16 v[96:99], v[144:147], v[198:201], v[96:99]
	v_mfma_f32_16x16x32_bf16 v[88:91], v[158:161], v[198:201], v[88:91]
	v_mfma_f32_16x16x32_bf16 v[80:83], v[144:147], v[206:209], v[80:83]
	v_mfma_f32_16x16x32_bf16 v[72:75], v[158:161], v[206:209], v[72:75]
	v_mfma_f32_16x16x32_bf16 v[124:127], v[154:157], v[186:189], v[124:127]
	v_mfma_f32_16x16x32_bf16 v[120:123], v[162:165], v[186:189], v[120:123]
	v_mfma_f32_16x16x32_bf16 v[112:115], v[154:157], v[194:197], v[112:115]
	v_mfma_f32_16x16x32_bf16 v[104:107], v[162:165], v[194:197], v[104:107]
	v_mfma_f32_16x16x32_bf16 v[96:99], v[154:157], v[202:205], v[96:99]
	v_mfma_f32_16x16x32_bf16 v[88:91], v[162:165], v[202:205], v[88:91]
	v_mfma_f32_16x16x32_bf16 v[80:83], v[154:157], v[210:213], v[80:83]
	v_mfma_f32_16x16x32_bf16 v[72:75], v[162:165], v[210:213], v[72:75]
	v_mfma_f32_16x16x32_bf16 v[116:119], v[166:169], v[182:185], v[116:119]
	v_mfma_f32_16x16x32_bf16 v[108:111], v[174:177], v[182:185], v[108:111]
	v_mfma_f32_16x16x32_bf16 v[100:103], v[166:169], v[190:193], v[100:103]
	v_mfma_f32_16x16x32_bf16 v[92:95], v[174:177], v[190:193], v[92:95]
	v_mfma_f32_16x16x32_bf16 v[84:87], v[166:169], v[198:201], v[84:87]
	v_mfma_f32_16x16x32_bf16 v[76:79], v[174:177], v[198:201], v[76:79]
	v_mfma_f32_16x16x32_bf16 v[68:71], v[166:169], v[206:209], v[68:71]
	v_mfma_f32_16x16x32_bf16 v[64:67], v[174:177], v[206:209], v[64:67]
	v_mfma_f32_16x16x32_bf16 v[116:119], v[170:173], v[186:189], v[116:119]
	v_mfma_f32_16x16x32_bf16 v[108:111], v[178:181], v[186:189], v[108:111]
	v_mfma_f32_16x16x32_bf16 v[100:103], v[170:173], v[194:197], v[100:103]
	v_mfma_f32_16x16x32_bf16 v[92:95], v[178:181], v[194:197], v[92:95]
	v_mfma_f32_16x16x32_bf16 v[84:87], v[170:173], v[202:205], v[84:87]
	v_mfma_f32_16x16x32_bf16 v[76:79], v[178:181], v[202:205], v[76:79]
	v_mfma_f32_16x16x32_bf16 v[68:71], v[170:173], v[210:213], v[68:71]
	v_mfma_f32_16x16x32_bf16 v[64:67], v[178:181], v[210:213], v[64:67]
	s_setprio 0
	s_barrier
	s_add_i32 s30, s53, s36
	s_mov_b32 m0, s30
	s_nop 0
	global_load_lds_dwordx4 v130, s[98:99]
	s_add_i32 m0, s30, 0x2000
	s_add_u32 s28, s28, 0x200080
	s_addc_u32 s29, s29, 0
	s_add_i32 s30, s54, s36
	global_load_lds_dwordx4 v134, s[98:99]
	s_mov_b32 m0, s30
	s_nop 0
	global_load_lds_dwordx4 v130, s[28:29]
	s_add_i32 m0, s30, 0x2000
	s_nop 0
	global_load_lds_dwordx4 v134, s[28:29]
	s_mov_b32 m0, s41
	s_nop 0
	global_load_lds_dwordx4 v128, s[100:101]
	s_mov_b32 m0, s42
	s_nop 0
	global_load_lds_dwordx4 v132, s[100:101]
	ds_read_b128 v[182:185], v153 offset:49152
	ds_read_b128 v[186:189], v153 offset:50176
	ds_read_b128 v[190:193], v153 offset:51200
	ds_read_b128 v[194:197], v153 offset:52224
	ds_read_b128 v[198:201], v153 offset:53248
	ds_read_b128 v[202:205], v153 offset:54272
	ds_read_b128 v[206:209], v153 offset:55296
	ds_read_b128 v[210:213], v153 offset:56320
	s_waitcnt vmcnt(8)
	s_waitcnt lgkmcnt(0)
	s_barrier
	s_setprio 1
	s_waitcnt lgkmcnt(0)
	v_mfma_f32_16x16x32_bf16 v[60:63], v[144:147], v[182:185], v[60:63]
	v_mfma_f32_16x16x32_bf16 v[56:59], v[158:161], v[182:185], v[56:59]
	v_mfma_f32_16x16x32_bf16 v[48:51], v[144:147], v[190:193], v[48:51]
	v_mfma_f32_16x16x32_bf16 v[40:43], v[158:161], v[190:193], v[40:43]
	v_mfma_f32_16x16x32_bf16 v[32:35], v[144:147], v[198:201], v[32:35]
	v_mfma_f32_16x16x32_bf16 v[24:27], v[158:161], v[198:201], v[24:27]
	v_mfma_f32_16x16x32_bf16 v[16:19], v[144:147], v[206:209], v[16:19]
	v_mfma_f32_16x16x32_bf16 v[8:11], v[158:161], v[206:209], v[8:11]
	v_mfma_f32_16x16x32_bf16 v[60:63], v[154:157], v[186:189], v[60:63]
	v_mfma_f32_16x16x32_bf16 v[56:59], v[162:165], v[186:189], v[56:59]
	v_mfma_f32_16x16x32_bf16 v[48:51], v[154:157], v[194:197], v[48:51]
	v_mfma_f32_16x16x32_bf16 v[40:43], v[162:165], v[194:197], v[40:43]
	v_mfma_f32_16x16x32_bf16 v[32:35], v[154:157], v[202:205], v[32:35]
	v_mfma_f32_16x16x32_bf16 v[24:27], v[162:165], v[202:205], v[24:27]
	v_mfma_f32_16x16x32_bf16 v[16:19], v[154:157], v[210:213], v[16:19]
	v_mfma_f32_16x16x32_bf16 v[8:11], v[162:165], v[210:213], v[8:11]
	v_mfma_f32_16x16x32_bf16 v[52:55], v[166:169], v[182:185], v[52:55]
	v_mfma_f32_16x16x32_bf16 v[44:47], v[174:177], v[182:185], v[44:47]
	v_mfma_f32_16x16x32_bf16 v[36:39], v[166:169], v[190:193], v[36:39]
	v_mfma_f32_16x16x32_bf16 v[28:31], v[174:177], v[190:193], v[28:31]
	v_mfma_f32_16x16x32_bf16 v[20:23], v[166:169], v[198:201], v[20:23]
	v_mfma_f32_16x16x32_bf16 v[12:15], v[174:177], v[198:201], v[12:15]
	v_mfma_f32_16x16x32_bf16 v[4:7], v[166:169], v[206:209], v[4:7]
	v_mfma_f32_16x16x32_bf16 v[0:3], v[174:177], v[206:209], v[0:3]
	v_mfma_f32_16x16x32_bf16 v[52:55], v[170:173], v[186:189], v[52:55]
	v_mfma_f32_16x16x32_bf16 v[44:47], v[178:181], v[186:189], v[44:47]
	v_mfma_f32_16x16x32_bf16 v[36:39], v[170:173], v[194:197], v[36:39]
	v_mfma_f32_16x16x32_bf16 v[28:31], v[178:181], v[194:197], v[28:31]
	v_mfma_f32_16x16x32_bf16 v[20:23], v[170:173], v[202:205], v[20:23]
	v_mfma_f32_16x16x32_bf16 v[12:15], v[178:181], v[202:205], v[12:15]
	v_mfma_f32_16x16x32_bf16 v[4:7], v[170:173], v[210:213], v[4:7]
	v_mfma_f32_16x16x32_bf16 v[0:3], v[178:181], v[210:213], v[0:3]
	s_setprio 0
	s_barrier
	s_add_i32 s52, s52, 2
	s_add_u32 s26, s26, 0x100
	s_addc_u32 s27, s27, 0
	s_add_u32 s50, s50, 0x100
	s_addc_u32 s51, s51, 0
	s_cmpk_gt_u32 s52, 0x7d
	s_cbranch_scc0 .LBB0_996
	s_and_b64 vcc, exec, s[14:15]
	s_cbranch_vccz .LBB0_999
	s_barrier
